# A9: A8 + RWKV scan reduces y once per 4 tokens (two tokens per register via bank-masked DPP adds), 2 LDS writes per 4 tokens
# baseline (speedup 1.0000x reference)
.LBB0_203:
	s_andn2_saveexec_b64 s[0:1], s[8:9]
	s_cbranch_execz .LBB0_184
	s_waitcnt lgkmcnt(0)
	s_barrier
	v_readlane_b32 s2, v251, 27
	v_and_b32_e32 v78, 15, v0
	v_lshrrev_b32_e32 v79, 4, v0
	s_nop 1
	v_lshl_add_u32 v103, v78, 4, s2
	v_lshl_add_u32 v38, v78, 5, s2
	v_bfe_u32 v81, v78, 2, 1
	v_lshlrev_b32_e32 v80, 1, v79
	v_add_u32_e32 v80, v80, v81
	v_lshl_add_u32 v77, s17, 5, v80
	v_xor_b32_e32 v40, 1, v77
	v_lshl_add_u32 v75, v77, 3, s2
	v_add_u32_e32 v75, 0xa000, v75
	v_lshl_add_u32 v37, v40, 3, s2
	v_add_u32_e32 v37, 0xa000, v37
	v_lshl_add_u32 v80, v80, 2, s2
	v_add_u32_e32 v80, 0x1c000, v80
	v_lshl_add_u32 v79, v0, 2, s2
	v_add_u32_e32 v79, 0x1e000, v79
	v_and_b32_e32 v81, 8, v78
	v_lshl_add_u32 v80, v81, 4, v80
	v_and_b32_e32 v81, 3, v78
	v_cmp_eq_u32_e32 vcc, 0, v81
	s_nop 3
	v_cndmask_b32_e32 v76, v79, v80, vcc
	v_mov_b32_e32 v20, 0
	v_mov_b32_e32 v21, 0
	v_mov_b32_e32 v22, 0
	v_mov_b32_e32 v23, 0
	v_mov_b32_e32 v24, 0
	v_mov_b32_e32 v25, 0
	v_mov_b32_e32 v26, 0
	v_mov_b32_e32 v27, 0
	s_setprio 3
	s_mov_b32 s8, 0
	s_waitcnt vmcnt(0)
.Lrw_scan_loop:
	s_and_b32 s2, s8, 1
	s_mul_i32 s3, s2, 0xe000
	s_lshl_b32 s2, s2, 12
	v_add_u32_e32 v195, s3, v103
	v_add_u32_e32 v33, s3, v38
	v_add_u32_e32 v196, s3, v75
	v_add_u32_e32 v36, s3, v37
	v_add_u32_e32 v102, s2, v76
	ds_read_b128 v[140:143], v195 offset:0
	ds_read_b128 v[152:155], v195 offset:8192
	ds_read_b128 v[176:179], v195 offset:16384
	ds_read_b128 v[84:87], v195 offset:32768
	ds_read_b64 v[4:5], v196 offset:0
	ds_read_b64 v[6:7], v36 offset:0
	ds_read_b128 v[144:147], v195 offset:256
	ds_read_b128 v[156:159], v195 offset:8448
	ds_read_b128 v[180:183], v195 offset:16640
	ds_read_b128 v[88:91], v195 offset:33024
	ds_read_b64 v[8:9], v196 offset:512
	ds_read_b64 v[10:11], v36 offset:512
	s_waitcnt lgkmcnt(6)
	v_pk_mul_f32 v[46:47], v[24:25], v[140:141] op_sel_hi:[0,1]
	v_pk_mul_f32 v[34:35], v[20:21], v[140:141] op_sel_hi:[0,1]
	v_pk_fma_f32 v[46:47], v[24:25], v[142:143], v[46:47] op_sel:[1,0,0] op_sel_hi:[1,1,1]
	v_pk_fma_f32 v[34:35], v[20:21], v[142:143], v[34:35] op_sel:[1,0,0] op_sel_hi:[1,1,1]
	v_pk_fma_f32 v[46:47], v[26:27], v[152:153], v[46:47] op_sel_hi:[0,1,1]
	v_pk_fma_f32 v[34:35], v[22:23], v[152:153], v[34:35] op_sel_hi:[0,1,1]
	v_pk_fma_f32 v[46:47], v[26:27], v[154:155], v[46:47] op_sel:[1,0,0] op_sel_hi:[1,1,1]
	v_pk_fma_f32 v[34:35], v[22:23], v[154:155], v[34:35] op_sel:[1,0,0] op_sel_hi:[1,1,1]
	v_pk_fma_f32 v[20:21], v[176:177], v[4:5], v[20:21] op_sel_hi:[1,0,1]
	v_add_f32_dpp v28, v46, v34 row_half_mirror row_mask:0xf bank_mask:0xf
	v_add_f32_dpp v148, v47, v35 row_half_mirror row_mask:0xf bank_mask:0xf
	v_pk_fma_f32 v[22:23], v[178:179], v[4:5], v[22:23] op_sel_hi:[1,0,1]
	v_add_f32_dpp v28, v28, v28 row_ror:8 row_mask:0xf bank_mask:0xf
	v_pk_fma_f32 v[24:25], v[176:177], v[6:7], v[24:25] op_sel_hi:[1,0,1]
	v_pk_fma_f32 v[26:27], v[178:179], v[6:7], v[26:27] op_sel_hi:[1,0,1]
	v_add_f32_dpp v28, v28, v28 quad_perm:[1,0,3,2] row_mask:0xf bank_mask:0xf
	v_fmac_f32_e32 v148, 0x3e000000, v5
	s_nop 0
	v_add_f32_dpp v28, v28, v28 quad_perm:[2,3,0,1] row_mask:0xf bank_mask:0xf
	v_pk_fma_f32 v[20:21], v[84:85], v[28:29], v[20:21] op_sel_hi:[1,0,1] neg_lo:[0,1,0] neg_hi:[0,1,0]
	v_pk_fma_f32 v[22:23], v[86:87], v[28:29], v[22:23] op_sel_hi:[1,0,1] neg_lo:[0,1,0] neg_hi:[0,1,0]
	v_mov_b32_dpp v30, v28 row_half_mirror row_mask:0xf bank_mask:0xf
	v_pk_fma_f32 v[24:25], v[84:85], v[30:31], v[24:25] op_sel_hi:[1,0,1] neg_lo:[0,1,0] neg_hi:[0,1,0]
	v_pk_fma_f32 v[26:27], v[86:87], v[30:31], v[26:27] op_sel_hi:[1,0,1] neg_lo:[0,1,0] neg_hi:[0,1,0]
	ds_read_b128 v[140:143], v195 offset:512
	ds_read_b128 v[152:155], v195 offset:8704
	ds_read_b128 v[176:179], v195 offset:16896
	ds_read_b128 v[84:87], v195 offset:33280
	ds_read_b64 v[4:5], v196 offset:1024
	ds_read_b64 v[6:7], v36 offset:1024
	s_waitcnt lgkmcnt(6)
	v_pk_mul_f32 v[46:47], v[24:25], v[144:145] op_sel_hi:[0,1]
	v_pk_mul_f32 v[34:35], v[20:21], v[144:145] op_sel_hi:[0,1]
	v_pk_fma_f32 v[46:47], v[24:25], v[146:147], v[46:47] op_sel:[1,0,0] op_sel_hi:[1,1,1]
	v_pk_fma_f32 v[34:35], v[20:21], v[146:147], v[34:35] op_sel:[1,0,0] op_sel_hi:[1,1,1]
	v_pk_fma_f32 v[46:47], v[26:27], v[156:157], v[46:47] op_sel_hi:[0,1,1]
	v_pk_fma_f32 v[34:35], v[22:23], v[156:157], v[34:35] op_sel_hi:[0,1,1]
	v_pk_fma_f32 v[46:47], v[26:27], v[158:159], v[46:47] op_sel:[1,0,0] op_sel_hi:[1,1,1]
	v_pk_fma_f32 v[34:35], v[22:23], v[158:159], v[34:35] op_sel:[1,0,0] op_sel_hi:[1,1,1]
	v_pk_fma_f32 v[20:21], v[180:181], v[8:9], v[20:21] op_sel_hi:[1,0,1]
	v_add_f32_dpp v28, v46, v34 row_half_mirror row_mask:0xf bank_mask:0xf
	v_add_f32_dpp v149, v47, v35 row_half_mirror row_mask:0xf bank_mask:0xf
	v_pk_fma_f32 v[22:23], v[182:183], v[8:9], v[22:23] op_sel_hi:[1,0,1]
	v_add_f32_dpp v28, v28, v28 row_ror:8 row_mask:0xf bank_mask:0xf
	v_pk_fma_f32 v[24:25], v[180:181], v[10:11], v[24:25] op_sel_hi:[1,0,1]
	v_pk_fma_f32 v[26:27], v[182:183], v[10:11], v[26:27] op_sel_hi:[1,0,1]
	v_add_f32_dpp v28, v28, v28 quad_perm:[1,0,3,2] row_mask:0xf bank_mask:0xf
	v_fmac_f32_e32 v149, 0x3e000000, v9
	s_nop 0
	v_add_f32_dpp v28, v28, v28 quad_perm:[2,3,0,1] row_mask:0xf bank_mask:0xf
	v_pk_fma_f32 v[20:21], v[88:89], v[28:29], v[20:21] op_sel_hi:[1,0,1] neg_lo:[0,1,0] neg_hi:[0,1,0]
	v_pk_fma_f32 v[22:23], v[90:91], v[28:29], v[22:23] op_sel_hi:[1,0,1] neg_lo:[0,1,0] neg_hi:[0,1,0]
	v_mov_b32_dpp v30, v28 row_half_mirror row_mask:0xf bank_mask:0xf
	v_pk_fma_f32 v[24:25], v[88:89], v[30:31], v[24:25] op_sel_hi:[1,0,1] neg_lo:[0,1,0] neg_hi:[0,1,0]
	v_pk_fma_f32 v[26:27], v[90:91], v[30:31], v[26:27] op_sel_hi:[1,0,1] neg_lo:[0,1,0] neg_hi:[0,1,0]
	ds_read_b128 v[144:147], v195 offset:768
	ds_read_b128 v[156:159], v195 offset:8960
	ds_read_b128 v[168:171], v195 offset:25344
	ds_read_b128 v[180:183], v195 offset:17152
	ds_read_b128 v[88:91], v195 offset:33536
	ds_read_b64 v[8:9], v196 offset:1536
	ds_read_b64 v[10:11], v36 offset:1536
	s_waitcnt lgkmcnt(7)
	v_pk_mul_f32 v[46:47], v[24:25], v[140:141] op_sel_hi:[0,1]
	v_pk_mul_f32 v[34:35], v[20:21], v[140:141] op_sel_hi:[0,1]
	v_pk_fma_f32 v[46:47], v[24:25], v[142:143], v[46:47] op_sel:[1,0,0] op_sel_hi:[1,1,1]
	v_pk_fma_f32 v[34:35], v[20:21], v[142:143], v[34:35] op_sel:[1,0,0] op_sel_hi:[1,1,1]
	v_pk_fma_f32 v[46:47], v[26:27], v[152:153], v[46:47] op_sel_hi:[0,1,1]
	v_pk_fma_f32 v[34:35], v[22:23], v[152:153], v[34:35] op_sel_hi:[0,1,1]
	v_pk_fma_f32 v[46:47], v[26:27], v[154:155], v[46:47] op_sel:[1,0,0] op_sel_hi:[1,1,1]
	v_pk_fma_f32 v[34:35], v[22:23], v[154:155], v[34:35] op_sel:[1,0,0] op_sel_hi:[1,1,1]
	v_pk_fma_f32 v[20:21], v[176:177], v[4:5], v[20:21] op_sel_hi:[1,0,1]
	v_add_f32_dpp v28, v46, v34 row_half_mirror row_mask:0xf bank_mask:0xf
	v_add_f32_dpp v150, v47, v35 row_half_mirror row_mask:0xf bank_mask:0xf
	v_pk_fma_f32 v[22:23], v[178:179], v[4:5], v[22:23] op_sel_hi:[1,0,1]
	v_add_f32_dpp v28, v28, v28 row_ror:8 row_mask:0xf bank_mask:0xf
	v_pk_fma_f32 v[24:25], v[176:177], v[6:7], v[24:25] op_sel_hi:[1,0,1]
	v_pk_fma_f32 v[26:27], v[178:179], v[6:7], v[26:27] op_sel_hi:[1,0,1]
	v_add_f32_dpp v28, v28, v28 quad_perm:[1,0,3,2] row_mask:0xf bank_mask:0xf
	v_fmac_f32_e32 v150, 0x3e000000, v5
	s_nop 0
	v_add_f32_dpp v28, v28, v28 quad_perm:[2,3,0,1] row_mask:0xf bank_mask:0xf
	v_pk_fma_f32 v[20:21], v[84:85], v[28:29], v[20:21] op_sel_hi:[1,0,1] neg_lo:[0,1,0] neg_hi:[0,1,0]
	v_pk_fma_f32 v[22:23], v[86:87], v[28:29], v[22:23] op_sel_hi:[1,0,1] neg_lo:[0,1,0] neg_hi:[0,1,0]
	v_mov_b32_dpp v30, v28 row_half_mirror row_mask:0xf bank_mask:0xf
	v_pk_fma_f32 v[24:25], v[84:85], v[30:31], v[24:25] op_sel_hi:[1,0,1] neg_lo:[0,1,0] neg_hi:[0,1,0]
	v_pk_fma_f32 v[26:27], v[86:87], v[30:31], v[26:27] op_sel_hi:[1,0,1] neg_lo:[0,1,0] neg_hi:[0,1,0]
	ds_read_b128 v[140:143], v195 offset:1024
	ds_read_b128 v[152:155], v195 offset:9216
	ds_read_b128 v[176:179], v195 offset:17408
	ds_read_b128 v[84:87], v195 offset:33792
	ds_read_b64 v[4:5], v196 offset:2048
	ds_read_b64 v[6:7], v36 offset:2048
	s_waitcnt lgkmcnt(6)
	v_pk_mul_f32 v[46:47], v[24:25], v[144:145] op_sel_hi:[0,1]
	v_pk_mul_f32 v[34:35], v[20:21], v[144:145] op_sel_hi:[0,1]
	v_pk_fma_f32 v[46:47], v[24:25], v[146:147], v[46:47] op_sel:[1,0,0] op_sel_hi:[1,1,1]
	v_pk_fma_f32 v[34:35], v[20:21], v[146:147], v[34:35] op_sel:[1,0,0] op_sel_hi:[1,1,1]
	v_pk_fma_f32 v[46:47], v[26:27], v[156:157], v[46:47] op_sel_hi:[0,1,1]
	v_pk_fma_f32 v[34:35], v[22:23], v[156:157], v[34:35] op_sel_hi:[0,1,1]
	v_pk_fma_f32 v[46:47], v[26:27], v[158:159], v[46:47] op_sel:[1,0,0] op_sel_hi:[1,1,1]
	v_pk_fma_f32 v[34:35], v[22:23], v[158:159], v[34:35] op_sel:[1,0,0] op_sel_hi:[1,1,1]
	v_pk_mul_f32 v[20:21], v[20:21], v[168:169]
	v_add_f32_dpp v28, v46, v34 row_half_mirror row_mask:0xf bank_mask:0xf
	v_add_f32_dpp v151, v47, v35 row_half_mirror row_mask:0xf bank_mask:0xf
	v_pk_mul_f32 v[22:23], v[22:23], v[170:171]
	v_add_f32_dpp v28, v28, v28 row_ror:8 row_mask:0xf bank_mask:0xf
	v_pk_mul_f32 v[24:25], v[24:25], v[168:169]
	v_pk_mul_f32 v[26:27], v[26:27], v[170:171]
	v_add_f32_dpp v28, v28, v28 quad_perm:[1,0,3,2] row_mask:0xf bank_mask:0xf
	v_pk_fma_f32 v[20:21], v[180:181], v[8:9], v[20:21] op_sel_hi:[1,0,1]
	v_pk_fma_f32 v[22:23], v[182:183], v[8:9], v[22:23] op_sel_hi:[1,0,1]
	v_add_f32_dpp v28, v28, v28 quad_perm:[2,3,0,1] row_mask:0xf bank_mask:0xf
	v_pk_fma_f32 v[24:25], v[180:181], v[10:11], v[24:25] op_sel_hi:[1,0,1]
	v_pk_fma_f32 v[26:27], v[182:183], v[10:11], v[26:27] op_sel_hi:[1,0,1]
	v_mov_b32_dpp v30, v28 row_half_mirror row_mask:0xf bank_mask:0xf
	v_fmac_f32_e32 v151, 0x3e000000, v9
	v_pk_fma_f32 v[20:21], v[88:89], v[28:29], v[20:21] op_sel_hi:[1,0,1] neg_lo:[0,1,0] neg_hi:[0,1,0]
	v_pk_fma_f32 v[22:23], v[90:91], v[28:29], v[22:23] op_sel_hi:[1,0,1] neg_lo:[0,1,0] neg_hi:[0,1,0]
	v_pk_fma_f32 v[24:25], v[88:89], v[30:31], v[24:25] op_sel_hi:[1,0,1] neg_lo:[0,1,0] neg_hi:[0,1,0]
	v_pk_fma_f32 v[26:27], v[90:91], v[30:31], v[26:27] op_sel_hi:[1,0,1] neg_lo:[0,1,0] neg_hi:[0,1,0]
	v_add_f32_dpp v160, v148, v148 row_ror:8 row_mask:0xf bank_mask:0x3
	v_add_f32_dpp v160, v149, v149 row_ror:8 row_mask:0xf bank_mask:0xc
	v_add_f32_dpp v161, v150, v150 row_ror:8 row_mask:0xf bank_mask:0x3
	v_add_f32_dpp v161, v151, v151 row_ror:8 row_mask:0xf bank_mask:0xc
	v_add_f32_dpp v160, v160, v160 quad_perm:[1,0,3,2] row_mask:0xf bank_mask:0xf
	s_nop 0
	v_add_f32_dpp v161, v161, v161 quad_perm:[1,0,3,2] row_mask:0xf bank_mask:0xf
	v_add_f32_dpp v160, v160, v160 quad_perm:[2,3,0,1] row_mask:0xf bank_mask:0xf
	s_nop 0
	v_add_f32_dpp v161, v161, v161 quad_perm:[2,3,0,1] row_mask:0xf bank_mask:0xf
	ds_write_b32 v102, v160 offset:0
	ds_write_b32 v102, v161 offset:256
	ds_read_b128 v[144:147], v195 offset:1280
	ds_read_b128 v[156:159], v195 offset:9472
	ds_read_b128 v[180:183], v195 offset:17664
	ds_read_b128 v[88:91], v195 offset:34048
	ds_read_b64 v[8:9], v196 offset:2560
	ds_read_b64 v[10:11], v36 offset:2560
	s_waitcnt lgkmcnt(8)
	v_pk_mul_f32 v[46:47], v[24:25], v[140:141] op_sel_hi:[0,1]
	v_pk_mul_f32 v[34:35], v[20:21], v[140:141] op_sel_hi:[0,1]
	v_pk_fma_f32 v[46:47], v[24:25], v[142:143], v[46:47] op_sel:[1,0,0] op_sel_hi:[1,1,1]
	v_pk_fma_f32 v[34:35], v[20:21], v[142:143], v[34:35] op_sel:[1,0,0] op_sel_hi:[1,1,1]
	v_pk_fma_f32 v[46:47], v[26:27], v[152:153], v[46:47] op_sel_hi:[0,1,1]
	v_pk_fma_f32 v[34:35], v[22:23], v[152:153], v[34:35] op_sel_hi:[0,1,1]
	v_pk_fma_f32 v[46:47], v[26:27], v[154:155], v[46:47] op_sel:[1,0,0] op_sel_hi:[1,1,1]
	v_pk_fma_f32 v[34:35], v[22:23], v[154:155], v[34:35] op_sel:[1,0,0] op_sel_hi:[1,1,1]
	v_pk_fma_f32 v[20:21], v[176:177], v[4:5], v[20:21] op_sel_hi:[1,0,1]
	v_add_f32_dpp v28, v46, v34 row_half_mirror row_mask:0xf bank_mask:0xf
	v_add_f32_dpp v148, v47, v35 row_half_mirror row_mask:0xf bank_mask:0xf
	v_pk_fma_f32 v[22:23], v[178:179], v[4:5], v[22:23] op_sel_hi:[1,0,1]
	v_add_f32_dpp v28, v28, v28 row_ror:8 row_mask:0xf bank_mask:0xf
	v_pk_fma_f32 v[24:25], v[176:177], v[6:7], v[24:25] op_sel_hi:[1,0,1]
	v_pk_fma_f32 v[26:27], v[178:179], v[6:7], v[26:27] op_sel_hi:[1,0,1]
	v_add_f32_dpp v28, v28, v28 quad_perm:[1,0,3,2] row_mask:0xf bank_mask:0xf
	v_fmac_f32_e32 v148, 0x3e000000, v5
	s_nop 0
	v_add_f32_dpp v28, v28, v28 quad_perm:[2,3,0,1] row_mask:0xf bank_mask:0xf
	v_pk_fma_f32 v[20:21], v[84:85], v[28:29], v[20:21] op_sel_hi:[1,0,1] neg_lo:[0,1,0] neg_hi:[0,1,0]
	v_pk_fma_f32 v[22:23], v[86:87], v[28:29], v[22:23] op_sel_hi:[1,0,1] neg_lo:[0,1,0] neg_hi:[0,1,0]
	v_mov_b32_dpp v30, v28 row_half_mirror row_mask:0xf bank_mask:0xf
	v_pk_fma_f32 v[24:25], v[84:85], v[30:31], v[24:25] op_sel_hi:[1,0,1] neg_lo:[0,1,0] neg_hi:[0,1,0]
	v_pk_fma_f32 v[26:27], v[86:87], v[30:31], v[26:27] op_sel_hi:[1,0,1] neg_lo:[0,1,0] neg_hi:[0,1,0]
	ds_read_b128 v[140:143], v195 offset:1536
	ds_read_b128 v[152:155], v195 offset:9728
	ds_read_b128 v[176:179], v195 offset:17920
	ds_read_b128 v[84:87], v195 offset:34304
	ds_read_b64 v[4:5], v196 offset:3072
	ds_read_b64 v[6:7], v36 offset:3072
	s_waitcnt lgkmcnt(6)
	v_pk_mul_f32 v[46:47], v[24:25], v[144:145] op_sel_hi:[0,1]
	v_pk_mul_f32 v[34:35], v[20:21], v[144:145] op_sel_hi:[0,1]
	v_pk_fma_f32 v[46:47], v[24:25], v[146:147], v[46:47] op_sel:[1,0,0] op_sel_hi:[1,1,1]
	v_pk_fma_f32 v[34:35], v[20:21], v[146:147], v[34:35] op_sel:[1,0,0] op_sel_hi:[1,1,1]
	v_pk_fma_f32 v[46:47], v[26:27], v[156:157], v[46:47] op_sel_hi:[0,1,1]
	v_pk_fma_f32 v[34:35], v[22:23], v[156:157], v[34:35] op_sel_hi:[0,1,1]
	v_pk_fma_f32 v[46:47], v[26:27], v[158:159], v[46:47] op_sel:[1,0,0] op_sel_hi:[1,1,1]
	v_pk_fma_f32 v[34:35], v[22:23], v[158:159], v[34:35] op_sel:[1,0,0] op_sel_hi:[1,1,1]
	v_pk_fma_f32 v[20:21], v[180:181], v[8:9], v[20:21] op_sel_hi:[1,0,1]
	v_add_f32_dpp v28, v46, v34 row_half_mirror row_mask:0xf bank_mask:0xf
	v_add_f32_dpp v149, v47, v35 row_half_mirror row_mask:0xf bank_mask:0xf
	v_pk_fma_f32 v[22:23], v[182:183], v[8:9], v[22:23] op_sel_hi:[1,0,1]
	v_add_f32_dpp v28, v28, v28 row_ror:8 row_mask:0xf bank_mask:0xf
	v_pk_fma_f32 v[24:25], v[180:181], v[10:11], v[24:25] op_sel_hi:[1,0,1]
	v_pk_fma_f32 v[26:27], v[182:183], v[10:11], v[26:27] op_sel_hi:[1,0,1]
	v_add_f32_dpp v28, v28, v28 quad_perm:[1,0,3,2] row_mask:0xf bank_mask:0xf
	v_fmac_f32_e32 v149, 0x3e000000, v9
	s_nop 0
	v_add_f32_dpp v28, v28, v28 quad_perm:[2,3,0,1] row_mask:0xf bank_mask:0xf
	v_pk_fma_f32 v[20:21], v[88:89], v[28:29], v[20:21] op_sel_hi:[1,0,1] neg_lo:[0,1,0] neg_hi:[0,1,0]
	v_pk_fma_f32 v[22:23], v[90:91], v[28:29], v[22:23] op_sel_hi:[1,0,1] neg_lo:[0,1,0] neg_hi:[0,1,0]
	v_mov_b32_dpp v30, v28 row_half_mirror row_mask:0xf bank_mask:0xf
	v_pk_fma_f32 v[24:25], v[88:89], v[30:31], v[24:25] op_sel_hi:[1,0,1] neg_lo:[0,1,0] neg_hi:[0,1,0]
	v_pk_fma_f32 v[26:27], v[90:91], v[30:31], v[26:27] op_sel_hi:[1,0,1] neg_lo:[0,1,0] neg_hi:[0,1,0]
	ds_read_b128 v[144:147], v195 offset:1792
	ds_read_b128 v[156:159], v195 offset:9984
	ds_read_b128 v[168:171], v195 offset:26368
	ds_read_b128 v[180:183], v195 offset:18176
	ds_read_b128 v[88:91], v195 offset:34560
	ds_read_b64 v[8:9], v196 offset:3584
	ds_read_b64 v[10:11], v36 offset:3584
	s_waitcnt lgkmcnt(7)
	v_pk_mul_f32 v[46:47], v[24:25], v[140:141] op_sel_hi:[0,1]
	v_pk_mul_f32 v[34:35], v[20:21], v[140:141] op_sel_hi:[0,1]
	v_pk_fma_f32 v[46:47], v[24:25], v[142:143], v[46:47] op_sel:[1,0,0] op_sel_hi:[1,1,1]
	v_pk_fma_f32 v[34:35], v[20:21], v[142:143], v[34:35] op_sel:[1,0,0] op_sel_hi:[1,1,1]
	v_pk_fma_f32 v[46:47], v[26:27], v[152:153], v[46:47] op_sel_hi:[0,1,1]
	v_pk_fma_f32 v[34:35], v[22:23], v[152:153], v[34:35] op_sel_hi:[0,1,1]
	v_pk_fma_f32 v[46:47], v[26:27], v[154:155], v[46:47] op_sel:[1,0,0] op_sel_hi:[1,1,1]
	v_pk_fma_f32 v[34:35], v[22:23], v[154:155], v[34:35] op_sel:[1,0,0] op_sel_hi:[1,1,1]
	v_pk_fma_f32 v[20:21], v[176:177], v[4:5], v[20:21] op_sel_hi:[1,0,1]
	v_add_f32_dpp v28, v46, v34 row_half_mirror row_mask:0xf bank_mask:0xf
	v_add_f32_dpp v150, v47, v35 row_half_mirror row_mask:0xf bank_mask:0xf
	v_pk_fma_f32 v[22:23], v[178:179], v[4:5], v[22:23] op_sel_hi:[1,0,1]
	v_add_f32_dpp v28, v28, v28 row_ror:8 row_mask:0xf bank_mask:0xf
	v_pk_fma_f32 v[24:25], v[176:177], v[6:7], v[24:25] op_sel_hi:[1,0,1]
	v_pk_fma_f32 v[26:27], v[178:179], v[6:7], v[26:27] op_sel_hi:[1,0,1]
	v_add_f32_dpp v28, v28, v28 quad_perm:[1,0,3,2] row_mask:0xf bank_mask:0xf
	v_fmac_f32_e32 v150, 0x3e000000, v5
	s_nop 0
	v_add_f32_dpp v28, v28, v28 quad_perm:[2,3,0,1] row_mask:0xf bank_mask:0xf
	v_pk_fma_f32 v[20:21], v[84:85], v[28:29], v[20:21] op_sel_hi:[1,0,1] neg_lo:[0,1,0] neg_hi:[0,1,0]
	v_pk_fma_f32 v[22:23], v[86:87], v[28:29], v[22:23] op_sel_hi:[1,0,1] neg_lo:[0,1,0] neg_hi:[0,1,0]
	v_mov_b32_dpp v30, v28 row_half_mirror row_mask:0xf bank_mask:0xf
	v_pk_fma_f32 v[24:25], v[84:85], v[30:31], v[24:25] op_sel_hi:[1,0,1] neg_lo:[0,1,0] neg_hi:[0,1,0]
	v_pk_fma_f32 v[26:27], v[86:87], v[30:31], v[26:27] op_sel_hi:[1,0,1] neg_lo:[0,1,0] neg_hi:[0,1,0]
	ds_read_b128 v[140:143], v195 offset:2048
	ds_read_b128 v[152:155], v195 offset:10240
	ds_read_b128 v[176:179], v195 offset:18432
	ds_read_b128 v[84:87], v195 offset:34816
	ds_read_b64 v[4:5], v196 offset:4096
	ds_read_b64 v[6:7], v36 offset:4096
	s_waitcnt lgkmcnt(6)
	v_pk_mul_f32 v[46:47], v[24:25], v[144:145] op_sel_hi:[0,1]
	v_pk_mul_f32 v[34:35], v[20:21], v[144:145] op_sel_hi:[0,1]
	v_pk_fma_f32 v[46:47], v[24:25], v[146:147], v[46:47] op_sel:[1,0,0] op_sel_hi:[1,1,1]
	v_pk_fma_f32 v[34:35], v[20:21], v[146:147], v[34:35] op_sel:[1,0,0] op_sel_hi:[1,1,1]
	v_pk_fma_f32 v[46:47], v[26:27], v[156:157], v[46:47] op_sel_hi:[0,1,1]
	v_pk_fma_f32 v[34:35], v[22:23], v[156:157], v[34:35] op_sel_hi:[0,1,1]
	v_pk_fma_f32 v[46:47], v[26:27], v[158:159], v[46:47] op_sel:[1,0,0] op_sel_hi:[1,1,1]
	v_pk_fma_f32 v[34:35], v[22:23], v[158:159], v[34:35] op_sel:[1,0,0] op_sel_hi:[1,1,1]
	v_pk_mul_f32 v[20:21], v[20:21], v[168:169]
	v_add_f32_dpp v28, v46, v34 row_half_mirror row_mask:0xf bank_mask:0xf
	v_add_f32_dpp v151, v47, v35 row_half_mirror row_mask:0xf bank_mask:0xf
	v_pk_mul_f32 v[22:23], v[22:23], v[170:171]
	v_add_f32_dpp v28, v28, v28 row_ror:8 row_mask:0xf bank_mask:0xf
	v_pk_mul_f32 v[24:25], v[24:25], v[168:169]
	v_pk_mul_f32 v[26:27], v[26:27], v[170:171]
	v_add_f32_dpp v28, v28, v28 quad_perm:[1,0,3,2] row_mask:0xf bank_mask:0xf
	v_pk_fma_f32 v[20:21], v[180:181], v[8:9], v[20:21] op_sel_hi:[1,0,1]
	v_pk_fma_f32 v[22:23], v[182:183], v[8:9], v[22:23] op_sel_hi:[1,0,1]
	v_add_f32_dpp v28, v28, v28 quad_perm:[2,3,0,1] row_mask:0xf bank_mask:0xf
	v_pk_fma_f32 v[24:25], v[180:181], v[10:11], v[24:25] op_sel_hi:[1,0,1]
	v_pk_fma_f32 v[26:27], v[182:183], v[10:11], v[26:27] op_sel_hi:[1,0,1]
	v_mov_b32_dpp v30, v28 row_half_mirror row_mask:0xf bank_mask:0xf
	v_fmac_f32_e32 v151, 0x3e000000, v9
	v_pk_fma_f32 v[20:21], v[88:89], v[28:29], v[20:21] op_sel_hi:[1,0,1] neg_lo:[0,1,0] neg_hi:[0,1,0]
	v_pk_fma_f32 v[22:23], v[90:91], v[28:29], v[22:23] op_sel_hi:[1,0,1] neg_lo:[0,1,0] neg_hi:[0,1,0]
	v_pk_fma_f32 v[24:25], v[88:89], v[30:31], v[24:25] op_sel_hi:[1,0,1] neg_lo:[0,1,0] neg_hi:[0,1,0]
	v_pk_fma_f32 v[26:27], v[90:91], v[30:31], v[26:27] op_sel_hi:[1,0,1] neg_lo:[0,1,0] neg_hi:[0,1,0]
	v_add_f32_dpp v160, v148, v148 row_ror:8 row_mask:0xf bank_mask:0x3
	v_add_f32_dpp v160, v149, v149 row_ror:8 row_mask:0xf bank_mask:0xc
	v_add_f32_dpp v161, v150, v150 row_ror:8 row_mask:0xf bank_mask:0x3
	v_add_f32_dpp v161, v151, v151 row_ror:8 row_mask:0xf bank_mask:0xc
	v_add_f32_dpp v160, v160, v160 quad_perm:[1,0,3,2] row_mask:0xf bank_mask:0xf
	s_nop 0
	v_add_f32_dpp v161, v161, v161 quad_perm:[1,0,3,2] row_mask:0xf bank_mask:0xf
	v_add_f32_dpp v160, v160, v160 quad_perm:[2,3,0,1] row_mask:0xf bank_mask:0xf
	s_nop 0
	v_add_f32_dpp v161, v161, v161 quad_perm:[2,3,0,1] row_mask:0xf bank_mask:0xf
	ds_write_b32 v102, v160 offset:512
	ds_write_b32 v102, v161 offset:768
	ds_read_b128 v[144:147], v195 offset:2304
	ds_read_b128 v[156:159], v195 offset:10496
	ds_read_b128 v[180:183], v195 offset:18688
	ds_read_b128 v[88:91], v195 offset:35072
	ds_read_b64 v[8:9], v196 offset:4608
	ds_read_b64 v[10:11], v36 offset:4608
	s_waitcnt lgkmcnt(8)
	v_pk_mul_f32 v[46:47], v[24:25], v[140:141] op_sel_hi:[0,1]
	v_pk_mul_f32 v[34:35], v[20:21], v[140:141] op_sel_hi:[0,1]
	v_pk_fma_f32 v[46:47], v[24:25], v[142:143], v[46:47] op_sel:[1,0,0] op_sel_hi:[1,1,1]
	v_pk_fma_f32 v[34:35], v[20:21], v[142:143], v[34:35] op_sel:[1,0,0] op_sel_hi:[1,1,1]
	v_pk_fma_f32 v[46:47], v[26:27], v[152:153], v[46:47] op_sel_hi:[0,1,1]
	v_pk_fma_f32 v[34:35], v[22:23], v[152:153], v[34:35] op_sel_hi:[0,1,1]
	v_pk_fma_f32 v[46:47], v[26:27], v[154:155], v[46:47] op_sel:[1,0,0] op_sel_hi:[1,1,1]
	v_pk_fma_f32 v[34:35], v[22:23], v[154:155], v[34:35] op_sel:[1,0,0] op_sel_hi:[1,1,1]
	v_pk_fma_f32 v[20:21], v[176:177], v[4:5], v[20:21] op_sel_hi:[1,0,1]
	v_add_f32_dpp v28, v46, v34 row_half_mirror row_mask:0xf bank_mask:0xf
	v_add_f32_dpp v148, v47, v35 row_half_mirror row_mask:0xf bank_mask:0xf
	v_pk_fma_f32 v[22:23], v[178:179], v[4:5], v[22:23] op_sel_hi:[1,0,1]
	v_add_f32_dpp v28, v28, v28 row_ror:8 row_mask:0xf bank_mask:0xf
	v_pk_fma_f32 v[24:25], v[176:177], v[6:7], v[24:25] op_sel_hi:[1,0,1]
	v_pk_fma_f32 v[26:27], v[178:179], v[6:7], v[26:27] op_sel_hi:[1,0,1]
	v_add_f32_dpp v28, v28, v28 quad_perm:[1,0,3,2] row_mask:0xf bank_mask:0xf
	v_fmac_f32_e32 v148, 0x3e000000, v5
	s_nop 0
	v_add_f32_dpp v28, v28, v28 quad_perm:[2,3,0,1] row_mask:0xf bank_mask:0xf
	v_pk_fma_f32 v[20:21], v[84:85], v[28:29], v[20:21] op_sel_hi:[1,0,1] neg_lo:[0,1,0] neg_hi:[0,1,0]
	v_pk_fma_f32 v[22:23], v[86:87], v[28:29], v[22:23] op_sel_hi:[1,0,1] neg_lo:[0,1,0] neg_hi:[0,1,0]
	v_mov_b32_dpp v30, v28 row_half_mirror row_mask:0xf bank_mask:0xf
	v_pk_fma_f32 v[24:25], v[84:85], v[30:31], v[24:25] op_sel_hi:[1,0,1] neg_lo:[0,1,0] neg_hi:[0,1,0]
	v_pk_fma_f32 v[26:27], v[86:87], v[30:31], v[26:27] op_sel_hi:[1,0,1] neg_lo:[0,1,0] neg_hi:[0,1,0]
	ds_read_b128 v[140:143], v195 offset:2560
	ds_read_b128 v[152:155], v195 offset:10752
	ds_read_b128 v[176:179], v195 offset:18944
	ds_read_b128 v[84:87], v195 offset:35328
	ds_read_b64 v[4:5], v196 offset:5120
	ds_read_b64 v[6:7], v36 offset:5120
	s_waitcnt lgkmcnt(6)
	v_pk_mul_f32 v[46:47], v[24:25], v[144:145] op_sel_hi:[0,1]
	v_pk_mul_f32 v[34:35], v[20:21], v[144:145] op_sel_hi:[0,1]
	v_pk_fma_f32 v[46:47], v[24:25], v[146:147], v[46:47] op_sel:[1,0,0] op_sel_hi:[1,1,1]
	v_pk_fma_f32 v[34:35], v[20:21], v[146:147], v[34:35] op_sel:[1,0,0] op_sel_hi:[1,1,1]
	v_pk_fma_f32 v[46:47], v[26:27], v[156:157], v[46:47] op_sel_hi:[0,1,1]
	v_pk_fma_f32 v[34:35], v[22:23], v[156:157], v[34:35] op_sel_hi:[0,1,1]
	v_pk_fma_f32 v[46:47], v[26:27], v[158:159], v[46:47] op_sel:[1,0,0] op_sel_hi:[1,1,1]
	v_pk_fma_f32 v[34:35], v[22:23], v[158:159], v[34:35] op_sel:[1,0,0] op_sel_hi:[1,1,1]
	v_pk_fma_f32 v[20:21], v[180:181], v[8:9], v[20:21] op_sel_hi:[1,0,1]
	v_add_f32_dpp v28, v46, v34 row_half_mirror row_mask:0xf bank_mask:0xf
	v_add_f32_dpp v149, v47, v35 row_half_mirror row_mask:0xf bank_mask:0xf
	v_pk_fma_f32 v[22:23], v[182:183], v[8:9], v[22:23] op_sel_hi:[1,0,1]
	v_add_f32_dpp v28, v28, v28 row_ror:8 row_mask:0xf bank_mask:0xf
	v_pk_fma_f32 v[24:25], v[180:181], v[10:11], v[24:25] op_sel_hi:[1,0,1]
	v_pk_fma_f32 v[26:27], v[182:183], v[10:11], v[26:27] op_sel_hi:[1,0,1]
	v_add_f32_dpp v28, v28, v28 quad_perm:[1,0,3,2] row_mask:0xf bank_mask:0xf
	v_fmac_f32_e32 v149, 0x3e000000, v9
	s_nop 0
	v_add_f32_dpp v28, v28, v28 quad_perm:[2,3,0,1] row_mask:0xf bank_mask:0xf
	v_pk_fma_f32 v[20:21], v[88:89], v[28:29], v[20:21] op_sel_hi:[1,0,1] neg_lo:[0,1,0] neg_hi:[0,1,0]
	v_pk_fma_f32 v[22:23], v[90:91], v[28:29], v[22:23] op_sel_hi:[1,0,1] neg_lo:[0,1,0] neg_hi:[0,1,0]
	v_mov_b32_dpp v30, v28 row_half_mirror row_mask:0xf bank_mask:0xf
	v_pk_fma_f32 v[24:25], v[88:89], v[30:31], v[24:25] op_sel_hi:[1,0,1] neg_lo:[0,1,0] neg_hi:[0,1,0]
	v_pk_fma_f32 v[26:27], v[90:91], v[30:31], v[26:27] op_sel_hi:[1,0,1] neg_lo:[0,1,0] neg_hi:[0,1,0]
	ds_read_b128 v[144:147], v195 offset:2816
	ds_read_b128 v[156:159], v195 offset:11008
	ds_read_b128 v[168:171], v195 offset:27392
	ds_read_b128 v[180:183], v195 offset:19200
	ds_read_b128 v[88:91], v195 offset:35584
	ds_read_b64 v[8:9], v196 offset:5632
	ds_read_b64 v[10:11], v36 offset:5632
	s_waitcnt lgkmcnt(7)
	v_pk_mul_f32 v[46:47], v[24:25], v[140:141] op_sel_hi:[0,1]
	v_pk_mul_f32 v[34:35], v[20:21], v[140:141] op_sel_hi:[0,1]
	v_pk_fma_f32 v[46:47], v[24:25], v[142:143], v[46:47] op_sel:[1,0,0] op_sel_hi:[1,1,1]
	v_pk_fma_f32 v[34:35], v[20:21], v[142:143], v[34:35] op_sel:[1,0,0] op_sel_hi:[1,1,1]
	v_pk_fma_f32 v[46:47], v[26:27], v[152:153], v[46:47] op_sel_hi:[0,1,1]
	v_pk_fma_f32 v[34:35], v[22:23], v[152:153], v[34:35] op_sel_hi:[0,1,1]
	v_pk_fma_f32 v[46:47], v[26:27], v[154:155], v[46:47] op_sel:[1,0,0] op_sel_hi:[1,1,1]
	v_pk_fma_f32 v[34:35], v[22:23], v[154:155], v[34:35] op_sel:[1,0,0] op_sel_hi:[1,1,1]
	v_pk_fma_f32 v[20:21], v[176:177], v[4:5], v[20:21] op_sel_hi:[1,0,1]
	v_add_f32_dpp v28, v46, v34 row_half_mirror row_mask:0xf bank_mask:0xf
	v_add_f32_dpp v150, v47, v35 row_half_mirror row_mask:0xf bank_mask:0xf
	v_pk_fma_f32 v[22:23], v[178:179], v[4:5], v[22:23] op_sel_hi:[1,0,1]
	v_add_f32_dpp v28, v28, v28 row_ror:8 row_mask:0xf bank_mask:0xf
	v_pk_fma_f32 v[24:25], v[176:177], v[6:7], v[24:25] op_sel_hi:[1,0,1]
	v_pk_fma_f32 v[26:27], v[178:179], v[6:7], v[26:27] op_sel_hi:[1,0,1]
	v_add_f32_dpp v28, v28, v28 quad_perm:[1,0,3,2] row_mask:0xf bank_mask:0xf
	v_fmac_f32_e32 v150, 0x3e000000, v5
	s_nop 0
	v_add_f32_dpp v28, v28, v28 quad_perm:[2,3,0,1] row_mask:0xf bank_mask:0xf
	v_pk_fma_f32 v[20:21], v[84:85], v[28:29], v[20:21] op_sel_hi:[1,0,1] neg_lo:[0,1,0] neg_hi:[0,1,0]
	v_pk_fma_f32 v[22:23], v[86:87], v[28:29], v[22:23] op_sel_hi:[1,0,1] neg_lo:[0,1,0] neg_hi:[0,1,0]
	v_mov_b32_dpp v30, v28 row_half_mirror row_mask:0xf bank_mask:0xf
	v_pk_fma_f32 v[24:25], v[84:85], v[30:31], v[24:25] op_sel_hi:[1,0,1] neg_lo:[0,1,0] neg_hi:[0,1,0]
	v_pk_fma_f32 v[26:27], v[86:87], v[30:31], v[26:27] op_sel_hi:[1,0,1] neg_lo:[0,1,0] neg_hi:[0,1,0]
	ds_read_b128 v[140:143], v195 offset:3072
	ds_read_b128 v[152:155], v195 offset:11264
	ds_read_b128 v[176:179], v195 offset:19456
	ds_read_b128 v[84:87], v195 offset:35840
	ds_read_b64 v[4:5], v196 offset:6144
	ds_read_b64 v[6:7], v36 offset:6144
	s_waitcnt lgkmcnt(6)
	v_pk_mul_f32 v[46:47], v[24:25], v[144:145] op_sel_hi:[0,1]
	v_pk_mul_f32 v[34:35], v[20:21], v[144:145] op_sel_hi:[0,1]
	v_pk_fma_f32 v[46:47], v[24:25], v[146:147], v[46:47] op_sel:[1,0,0] op_sel_hi:[1,1,1]
	v_pk_fma_f32 v[34:35], v[20:21], v[146:147], v[34:35] op_sel:[1,0,0] op_sel_hi:[1,1,1]
	v_pk_fma_f32 v[46:47], v[26:27], v[156:157], v[46:47] op_sel_hi:[0,1,1]
	v_pk_fma_f32 v[34:35], v[22:23], v[156:157], v[34:35] op_sel_hi:[0,1,1]
	v_pk_fma_f32 v[46:47], v[26:27], v[158:159], v[46:47] op_sel:[1,0,0] op_sel_hi:[1,1,1]
	v_pk_fma_f32 v[34:35], v[22:23], v[158:159], v[34:35] op_sel:[1,0,0] op_sel_hi:[1,1,1]
	v_pk_mul_f32 v[20:21], v[20:21], v[168:169]
	v_add_f32_dpp v28, v46, v34 row_half_mirror row_mask:0xf bank_mask:0xf
	v_add_f32_dpp v151, v47, v35 row_half_mirror row_mask:0xf bank_mask:0xf
	v_pk_mul_f32 v[22:23], v[22:23], v[170:171]
	v_add_f32_dpp v28, v28, v28 row_ror:8 row_mask:0xf bank_mask:0xf
	v_pk_mul_f32 v[24:25], v[24:25], v[168:169]
	v_pk_mul_f32 v[26:27], v[26:27], v[170:171]
	v_add_f32_dpp v28, v28, v28 quad_perm:[1,0,3,2] row_mask:0xf bank_mask:0xf
	v_pk_fma_f32 v[20:21], v[180:181], v[8:9], v[20:21] op_sel_hi:[1,0,1]
	v_pk_fma_f32 v[22:23], v[182:183], v[8:9], v[22:23] op_sel_hi:[1,0,1]
	v_add_f32_dpp v28, v28, v28 quad_perm:[2,3,0,1] row_mask:0xf bank_mask:0xf
	v_pk_fma_f32 v[24:25], v[180:181], v[10:11], v[24:25] op_sel_hi:[1,0,1]
	v_pk_fma_f32 v[26:27], v[182:183], v[10:11], v[26:27] op_sel_hi:[1,0,1]
	v_mov_b32_dpp v30, v28 row_half_mirror row_mask:0xf bank_mask:0xf
	v_fmac_f32_e32 v151, 0x3e000000, v9
	v_pk_fma_f32 v[20:21], v[88:89], v[28:29], v[20:21] op_sel_hi:[1,0,1] neg_lo:[0,1,0] neg_hi:[0,1,0]
	v_pk_fma_f32 v[22:23], v[90:91], v[28:29], v[22:23] op_sel_hi:[1,0,1] neg_lo:[0,1,0] neg_hi:[0,1,0]
	v_pk_fma_f32 v[24:25], v[88:89], v[30:31], v[24:25] op_sel_hi:[1,0,1] neg_lo:[0,1,0] neg_hi:[0,1,0]
	v_pk_fma_f32 v[26:27], v[90:91], v[30:31], v[26:27] op_sel_hi:[1,0,1] neg_lo:[0,1,0] neg_hi:[0,1,0]
	v_add_f32_dpp v160, v148, v148 row_ror:8 row_mask:0xf bank_mask:0x3
	v_add_f32_dpp v160, v149, v149 row_ror:8 row_mask:0xf bank_mask:0xc
	v_add_f32_dpp v161, v150, v150 row_ror:8 row_mask:0xf bank_mask:0x3
	v_add_f32_dpp v161, v151, v151 row_ror:8 row_mask:0xf bank_mask:0xc
	v_add_f32_dpp v160, v160, v160 quad_perm:[1,0,3,2] row_mask:0xf bank_mask:0xf
	s_nop 0
	v_add_f32_dpp v161, v161, v161 quad_perm:[1,0,3,2] row_mask:0xf bank_mask:0xf
	v_add_f32_dpp v160, v160, v160 quad_perm:[2,3,0,1] row_mask:0xf bank_mask:0xf
	s_nop 0
	v_add_f32_dpp v161, v161, v161 quad_perm:[2,3,0,1] row_mask:0xf bank_mask:0xf
	ds_write_b32 v102, v160 offset:1024
	ds_write_b32 v102, v161 offset:1280
	ds_read_b128 v[144:147], v195 offset:3328
	ds_read_b128 v[156:159], v195 offset:11520
	ds_read_b128 v[180:183], v195 offset:19712
	ds_read_b128 v[88:91], v195 offset:36096
	ds_read_b64 v[8:9], v196 offset:6656
	ds_read_b64 v[10:11], v36 offset:6656
	s_waitcnt lgkmcnt(8)
	v_pk_mul_f32 v[46:47], v[24:25], v[140:141] op_sel_hi:[0,1]
	v_pk_mul_f32 v[34:35], v[20:21], v[140:141] op_sel_hi:[0,1]
	v_pk_fma_f32 v[46:47], v[24:25], v[142:143], v[46:47] op_sel:[1,0,0] op_sel_hi:[1,1,1]
	v_pk_fma_f32 v[34:35], v[20:21], v[142:143], v[34:35] op_sel:[1,0,0] op_sel_hi:[1,1,1]
	v_pk_fma_f32 v[46:47], v[26:27], v[152:153], v[46:47] op_sel_hi:[0,1,1]
	v_pk_fma_f32 v[34:35], v[22:23], v[152:153], v[34:35] op_sel_hi:[0,1,1]
	v_pk_fma_f32 v[46:47], v[26:27], v[154:155], v[46:47] op_sel:[1,0,0] op_sel_hi:[1,1,1]
	v_pk_fma_f32 v[34:35], v[22:23], v[154:155], v[34:35] op_sel:[1,0,0] op_sel_hi:[1,1,1]
	v_pk_fma_f32 v[20:21], v[176:177], v[4:5], v[20:21] op_sel_hi:[1,0,1]
	v_add_f32_dpp v28, v46, v34 row_half_mirror row_mask:0xf bank_mask:0xf
	v_add_f32_dpp v148, v47, v35 row_half_mirror row_mask:0xf bank_mask:0xf
	v_pk_fma_f32 v[22:23], v[178:179], v[4:5], v[22:23] op_sel_hi:[1,0,1]
	v_add_f32_dpp v28, v28, v28 row_ror:8 row_mask:0xf bank_mask:0xf
	v_pk_fma_f32 v[24:25], v[176:177], v[6:7], v[24:25] op_sel_hi:[1,0,1]
	v_pk_fma_f32 v[26:27], v[178:179], v[6:7], v[26:27] op_sel_hi:[1,0,1]
	v_add_f32_dpp v28, v28, v28 quad_perm:[1,0,3,2] row_mask:0xf bank_mask:0xf
	v_fmac_f32_e32 v148, 0x3e000000, v5
	s_nop 0
	v_add_f32_dpp v28, v28, v28 quad_perm:[2,3,0,1] row_mask:0xf bank_mask:0xf
	v_pk_fma_f32 v[20:21], v[84:85], v[28:29], v[20:21] op_sel_hi:[1,0,1] neg_lo:[0,1,0] neg_hi:[0,1,0]
	v_pk_fma_f32 v[22:23], v[86:87], v[28:29], v[22:23] op_sel_hi:[1,0,1] neg_lo:[0,1,0] neg_hi:[0,1,0]
	v_mov_b32_dpp v30, v28 row_half_mirror row_mask:0xf bank_mask:0xf
	v_pk_fma_f32 v[24:25], v[84:85], v[30:31], v[24:25] op_sel_hi:[1,0,1] neg_lo:[0,1,0] neg_hi:[0,1,0]
	v_pk_fma_f32 v[26:27], v[86:87], v[30:31], v[26:27] op_sel_hi:[1,0,1] neg_lo:[0,1,0] neg_hi:[0,1,0]
	ds_read_b128 v[140:143], v195 offset:3584
	ds_read_b128 v[152:155], v195 offset:11776
	ds_read_b128 v[176:179], v195 offset:19968
	ds_read_b128 v[84:87], v195 offset:36352
	ds_read_b64 v[4:5], v196 offset:7168
	ds_read_b64 v[6:7], v36 offset:7168
	s_waitcnt lgkmcnt(6)
	v_pk_mul_f32 v[46:47], v[24:25], v[144:145] op_sel_hi:[0,1]
	v_pk_mul_f32 v[34:35], v[20:21], v[144:145] op_sel_hi:[0,1]
	v_pk_fma_f32 v[46:47], v[24:25], v[146:147], v[46:47] op_sel:[1,0,0] op_sel_hi:[1,1,1]
	v_pk_fma_f32 v[34:35], v[20:21], v[146:147], v[34:35] op_sel:[1,0,0] op_sel_hi:[1,1,1]
	v_pk_fma_f32 v[46:47], v[26:27], v[156:157], v[46:47] op_sel_hi:[0,1,1]
	v_pk_fma_f32 v[34:35], v[22:23], v[156:157], v[34:35] op_sel_hi:[0,1,1]
	v_pk_fma_f32 v[46:47], v[26:27], v[158:159], v[46:47] op_sel:[1,0,0] op_sel_hi:[1,1,1]
	v_pk_fma_f32 v[34:35], v[22:23], v[158:159], v[34:35] op_sel:[1,0,0] op_sel_hi:[1,1,1]
	v_pk_fma_f32 v[20:21], v[180:181], v[8:9], v[20:21] op_sel_hi:[1,0,1]
	v_add_f32_dpp v28, v46, v34 row_half_mirror row_mask:0xf bank_mask:0xf
	v_add_f32_dpp v149, v47, v35 row_half_mirror row_mask:0xf bank_mask:0xf
	v_pk_fma_f32 v[22:23], v[182:183], v[8:9], v[22:23] op_sel_hi:[1,0,1]
	v_add_f32_dpp v28, v28, v28 row_ror:8 row_mask:0xf bank_mask:0xf
	v_pk_fma_f32 v[24:25], v[180:181], v[10:11], v[24:25] op_sel_hi:[1,0,1]
	v_pk_fma_f32 v[26:27], v[182:183], v[10:11], v[26:27] op_sel_hi:[1,0,1]
	v_add_f32_dpp v28, v28, v28 quad_perm:[1,0,3,2] row_mask:0xf bank_mask:0xf
	v_fmac_f32_e32 v149, 0x3e000000, v9
	s_nop 0
	v_add_f32_dpp v28, v28, v28 quad_perm:[2,3,0,1] row_mask:0xf bank_mask:0xf
	v_pk_fma_f32 v[20:21], v[88:89], v[28:29], v[20:21] op_sel_hi:[1,0,1] neg_lo:[0,1,0] neg_hi:[0,1,0]
	v_pk_fma_f32 v[22:23], v[90:91], v[28:29], v[22:23] op_sel_hi:[1,0,1] neg_lo:[0,1,0] neg_hi:[0,1,0]
	v_mov_b32_dpp v30, v28 row_half_mirror row_mask:0xf bank_mask:0xf
	v_pk_fma_f32 v[24:25], v[88:89], v[30:31], v[24:25] op_sel_hi:[1,0,1] neg_lo:[0,1,0] neg_hi:[0,1,0]
	v_pk_fma_f32 v[26:27], v[90:91], v[30:31], v[26:27] op_sel_hi:[1,0,1] neg_lo:[0,1,0] neg_hi:[0,1,0]
	ds_read_b128 v[144:147], v195 offset:3840
	ds_read_b128 v[156:159], v195 offset:12032
	ds_read_b128 v[168:171], v195 offset:28416
	ds_read_b128 v[180:183], v195 offset:20224
	ds_read_b128 v[88:91], v195 offset:36608
	ds_read_b64 v[8:9], v196 offset:7680
	ds_read_b64 v[10:11], v36 offset:7680
	s_waitcnt lgkmcnt(7)
	v_pk_mul_f32 v[46:47], v[24:25], v[140:141] op_sel_hi:[0,1]
	v_pk_mul_f32 v[34:35], v[20:21], v[140:141] op_sel_hi:[0,1]
	v_pk_fma_f32 v[46:47], v[24:25], v[142:143], v[46:47] op_sel:[1,0,0] op_sel_hi:[1,1,1]
	v_pk_fma_f32 v[34:35], v[20:21], v[142:143], v[34:35] op_sel:[1,0,0] op_sel_hi:[1,1,1]
	v_pk_fma_f32 v[46:47], v[26:27], v[152:153], v[46:47] op_sel_hi:[0,1,1]
	v_pk_fma_f32 v[34:35], v[22:23], v[152:153], v[34:35] op_sel_hi:[0,1,1]
	v_pk_fma_f32 v[46:47], v[26:27], v[154:155], v[46:47] op_sel:[1,0,0] op_sel_hi:[1,1,1]
	v_pk_fma_f32 v[34:35], v[22:23], v[154:155], v[34:35] op_sel:[1,0,0] op_sel_hi:[1,1,1]
	v_pk_fma_f32 v[20:21], v[176:177], v[4:5], v[20:21] op_sel_hi:[1,0,1]
	v_add_f32_dpp v28, v46, v34 row_half_mirror row_mask:0xf bank_mask:0xf
	v_add_f32_dpp v150, v47, v35 row_half_mirror row_mask:0xf bank_mask:0xf
	v_pk_fma_f32 v[22:23], v[178:179], v[4:5], v[22:23] op_sel_hi:[1,0,1]
	v_add_f32_dpp v28, v28, v28 row_ror:8 row_mask:0xf bank_mask:0xf
	v_pk_fma_f32 v[24:25], v[176:177], v[6:7], v[24:25] op_sel_hi:[1,0,1]
	v_pk_fma_f32 v[26:27], v[178:179], v[6:7], v[26:27] op_sel_hi:[1,0,1]
	v_add_f32_dpp v28, v28, v28 quad_perm:[1,0,3,2] row_mask:0xf bank_mask:0xf
	v_fmac_f32_e32 v150, 0x3e000000, v5
	s_nop 0
	v_add_f32_dpp v28, v28, v28 quad_perm:[2,3,0,1] row_mask:0xf bank_mask:0xf
	v_pk_fma_f32 v[20:21], v[84:85], v[28:29], v[20:21] op_sel_hi:[1,0,1] neg_lo:[0,1,0] neg_hi:[0,1,0]
	v_pk_fma_f32 v[22:23], v[86:87], v[28:29], v[22:23] op_sel_hi:[1,0,1] neg_lo:[0,1,0] neg_hi:[0,1,0]
	v_mov_b32_dpp v30, v28 row_half_mirror row_mask:0xf bank_mask:0xf
	v_pk_fma_f32 v[24:25], v[84:85], v[30:31], v[24:25] op_sel_hi:[1,0,1] neg_lo:[0,1,0] neg_hi:[0,1,0]
	v_pk_fma_f32 v[26:27], v[86:87], v[30:31], v[26:27] op_sel_hi:[1,0,1] neg_lo:[0,1,0] neg_hi:[0,1,0]
	ds_read_b128 v[140:143], v195 offset:4096
	ds_read_b128 v[152:155], v195 offset:12288
	ds_read_b128 v[176:179], v195 offset:20480
	ds_read_b128 v[84:87], v195 offset:36864
	ds_read_b64 v[4:5], v196 offset:8192
	ds_read_b64 v[6:7], v36 offset:8192
	s_waitcnt lgkmcnt(6)
	v_pk_mul_f32 v[46:47], v[24:25], v[144:145] op_sel_hi:[0,1]
	v_pk_mul_f32 v[34:35], v[20:21], v[144:145] op_sel_hi:[0,1]
	v_pk_fma_f32 v[46:47], v[24:25], v[146:147], v[46:47] op_sel:[1,0,0] op_sel_hi:[1,1,1]
	v_pk_fma_f32 v[34:35], v[20:21], v[146:147], v[34:35] op_sel:[1,0,0] op_sel_hi:[1,1,1]
	v_pk_fma_f32 v[46:47], v[26:27], v[156:157], v[46:47] op_sel_hi:[0,1,1]
	v_pk_fma_f32 v[34:35], v[22:23], v[156:157], v[34:35] op_sel_hi:[0,1,1]
	v_pk_fma_f32 v[46:47], v[26:27], v[158:159], v[46:47] op_sel:[1,0,0] op_sel_hi:[1,1,1]
	v_pk_fma_f32 v[34:35], v[22:23], v[158:159], v[34:35] op_sel:[1,0,0] op_sel_hi:[1,1,1]
	v_pk_mul_f32 v[20:21], v[20:21], v[168:169]
	v_add_f32_dpp v28, v46, v34 row_half_mirror row_mask:0xf bank_mask:0xf
	v_add_f32_dpp v151, v47, v35 row_half_mirror row_mask:0xf bank_mask:0xf
	v_pk_mul_f32 v[22:23], v[22:23], v[170:171]
	v_add_f32_dpp v28, v28, v28 row_ror:8 row_mask:0xf bank_mask:0xf
	v_pk_mul_f32 v[24:25], v[24:25], v[168:169]
	v_pk_mul_f32 v[26:27], v[26:27], v[170:171]
	v_add_f32_dpp v28, v28, v28 quad_perm:[1,0,3,2] row_mask:0xf bank_mask:0xf
	v_pk_fma_f32 v[20:21], v[180:181], v[8:9], v[20:21] op_sel_hi:[1,0,1]
	v_pk_fma_f32 v[22:23], v[182:183], v[8:9], v[22:23] op_sel_hi:[1,0,1]
	v_add_f32_dpp v28, v28, v28 quad_perm:[2,3,0,1] row_mask:0xf bank_mask:0xf
	v_pk_fma_f32 v[24:25], v[180:181], v[10:11], v[24:25] op_sel_hi:[1,0,1]
	v_pk_fma_f32 v[26:27], v[182:183], v[10:11], v[26:27] op_sel_hi:[1,0,1]
	v_mov_b32_dpp v30, v28 row_half_mirror row_mask:0xf bank_mask:0xf
	v_fmac_f32_e32 v151, 0x3e000000, v9
	v_pk_fma_f32 v[20:21], v[88:89], v[28:29], v[20:21] op_sel_hi:[1,0,1] neg_lo:[0,1,0] neg_hi:[0,1,0]
	v_pk_fma_f32 v[22:23], v[90:91], v[28:29], v[22:23] op_sel_hi:[1,0,1] neg_lo:[0,1,0] neg_hi:[0,1,0]
	v_pk_fma_f32 v[24:25], v[88:89], v[30:31], v[24:25] op_sel_hi:[1,0,1] neg_lo:[0,1,0] neg_hi:[0,1,0]
	v_pk_fma_f32 v[26:27], v[90:91], v[30:31], v[26:27] op_sel_hi:[1,0,1] neg_lo:[0,1,0] neg_hi:[0,1,0]
	v_add_f32_dpp v160, v148, v148 row_ror:8 row_mask:0xf bank_mask:0x3
	v_add_f32_dpp v160, v149, v149 row_ror:8 row_mask:0xf bank_mask:0xc
	v_add_f32_dpp v161, v150, v150 row_ror:8 row_mask:0xf bank_mask:0x3
	v_add_f32_dpp v161, v151, v151 row_ror:8 row_mask:0xf bank_mask:0xc
	v_add_f32_dpp v160, v160, v160 quad_perm:[1,0,3,2] row_mask:0xf bank_mask:0xf
	s_nop 0
	v_add_f32_dpp v161, v161, v161 quad_perm:[1,0,3,2] row_mask:0xf bank_mask:0xf
	v_add_f32_dpp v160, v160, v160 quad_perm:[2,3,0,1] row_mask:0xf bank_mask:0xf
	s_nop 0
	v_add_f32_dpp v161, v161, v161 quad_perm:[2,3,0,1] row_mask:0xf bank_mask:0xf
	ds_write_b32 v102, v160 offset:1536
	ds_write_b32 v102, v161 offset:1792
	ds_read_b128 v[144:147], v195 offset:4352
	ds_read_b128 v[156:159], v195 offset:12544
	ds_read_b128 v[180:183], v195 offset:20736
	ds_read_b128 v[88:91], v195 offset:37120
	ds_read_b64 v[8:9], v196 offset:8704
	ds_read_b64 v[10:11], v36 offset:8704
	s_waitcnt lgkmcnt(8)
	v_pk_mul_f32 v[46:47], v[24:25], v[140:141] op_sel_hi:[0,1]
	v_pk_mul_f32 v[34:35], v[20:21], v[140:141] op_sel_hi:[0,1]
	v_pk_fma_f32 v[46:47], v[24:25], v[142:143], v[46:47] op_sel:[1,0,0] op_sel_hi:[1,1,1]
	v_pk_fma_f32 v[34:35], v[20:21], v[142:143], v[34:35] op_sel:[1,0,0] op_sel_hi:[1,1,1]
	v_pk_fma_f32 v[46:47], v[26:27], v[152:153], v[46:47] op_sel_hi:[0,1,1]
	v_pk_fma_f32 v[34:35], v[22:23], v[152:153], v[34:35] op_sel_hi:[0,1,1]
	v_pk_fma_f32 v[46:47], v[26:27], v[154:155], v[46:47] op_sel:[1,0,0] op_sel_hi:[1,1,1]
	v_pk_fma_f32 v[34:35], v[22:23], v[154:155], v[34:35] op_sel:[1,0,0] op_sel_hi:[1,1,1]
	v_pk_fma_f32 v[20:21], v[176:177], v[4:5], v[20:21] op_sel_hi:[1,0,1]
	v_add_f32_dpp v28, v46, v34 row_half_mirror row_mask:0xf bank_mask:0xf
	v_add_f32_dpp v148, v47, v35 row_half_mirror row_mask:0xf bank_mask:0xf
	v_pk_fma_f32 v[22:23], v[178:179], v[4:5], v[22:23] op_sel_hi:[1,0,1]
	v_add_f32_dpp v28, v28, v28 row_ror:8 row_mask:0xf bank_mask:0xf
	v_pk_fma_f32 v[24:25], v[176:177], v[6:7], v[24:25] op_sel_hi:[1,0,1]
	v_pk_fma_f32 v[26:27], v[178:179], v[6:7], v[26:27] op_sel_hi:[1,0,1]
	v_add_f32_dpp v28, v28, v28 quad_perm:[1,0,3,2] row_mask:0xf bank_mask:0xf
	v_fmac_f32_e32 v148, 0x3e000000, v5
	s_nop 0
	v_add_f32_dpp v28, v28, v28 quad_perm:[2,3,0,1] row_mask:0xf bank_mask:0xf
	v_pk_fma_f32 v[20:21], v[84:85], v[28:29], v[20:21] op_sel_hi:[1,0,1] neg_lo:[0,1,0] neg_hi:[0,1,0]
	v_pk_fma_f32 v[22:23], v[86:87], v[28:29], v[22:23] op_sel_hi:[1,0,1] neg_lo:[0,1,0] neg_hi:[0,1,0]
	v_mov_b32_dpp v30, v28 row_half_mirror row_mask:0xf bank_mask:0xf
	v_pk_fma_f32 v[24:25], v[84:85], v[30:31], v[24:25] op_sel_hi:[1,0,1] neg_lo:[0,1,0] neg_hi:[0,1,0]
	v_pk_fma_f32 v[26:27], v[86:87], v[30:31], v[26:27] op_sel_hi:[1,0,1] neg_lo:[0,1,0] neg_hi:[0,1,0]
	ds_read_b128 v[140:143], v195 offset:4608
	ds_read_b128 v[152:155], v195 offset:12800
	ds_read_b128 v[176:179], v195 offset:20992
	ds_read_b128 v[84:87], v195 offset:37376
	ds_read_b64 v[4:5], v196 offset:9216
	ds_read_b64 v[6:7], v36 offset:9216
	s_waitcnt lgkmcnt(6)
	v_pk_mul_f32 v[46:47], v[24:25], v[144:145] op_sel_hi:[0,1]
	v_pk_mul_f32 v[34:35], v[20:21], v[144:145] op_sel_hi:[0,1]
	v_pk_fma_f32 v[46:47], v[24:25], v[146:147], v[46:47] op_sel:[1,0,0] op_sel_hi:[1,1,1]
	v_pk_fma_f32 v[34:35], v[20:21], v[146:147], v[34:35] op_sel:[1,0,0] op_sel_hi:[1,1,1]
	v_pk_fma_f32 v[46:47], v[26:27], v[156:157], v[46:47] op_sel_hi:[0,1,1]
	v_pk_fma_f32 v[34:35], v[22:23], v[156:157], v[34:35] op_sel_hi:[0,1,1]
	v_pk_fma_f32 v[46:47], v[26:27], v[158:159], v[46:47] op_sel:[1,0,0] op_sel_hi:[1,1,1]
	v_pk_fma_f32 v[34:35], v[22:23], v[158:159], v[34:35] op_sel:[1,0,0] op_sel_hi:[1,1,1]
	v_pk_fma_f32 v[20:21], v[180:181], v[8:9], v[20:21] op_sel_hi:[1,0,1]
	v_add_f32_dpp v28, v46, v34 row_half_mirror row_mask:0xf bank_mask:0xf
	v_add_f32_dpp v149, v47, v35 row_half_mirror row_mask:0xf bank_mask:0xf
	v_pk_fma_f32 v[22:23], v[182:183], v[8:9], v[22:23] op_sel_hi:[1,0,1]
	v_add_f32_dpp v28, v28, v28 row_ror:8 row_mask:0xf bank_mask:0xf
	v_pk_fma_f32 v[24:25], v[180:181], v[10:11], v[24:25] op_sel_hi:[1,0,1]
	v_pk_fma_f32 v[26:27], v[182:183], v[10:11], v[26:27] op_sel_hi:[1,0,1]
	v_add_f32_dpp v28, v28, v28 quad_perm:[1,0,3,2] row_mask:0xf bank_mask:0xf
	v_fmac_f32_e32 v149, 0x3e000000, v9
	s_nop 0
	v_add_f32_dpp v28, v28, v28 quad_perm:[2,3,0,1] row_mask:0xf bank_mask:0xf
	v_pk_fma_f32 v[20:21], v[88:89], v[28:29], v[20:21] op_sel_hi:[1,0,1] neg_lo:[0,1,0] neg_hi:[0,1,0]
	v_pk_fma_f32 v[22:23], v[90:91], v[28:29], v[22:23] op_sel_hi:[1,0,1] neg_lo:[0,1,0] neg_hi:[0,1,0]
	v_mov_b32_dpp v30, v28 row_half_mirror row_mask:0xf bank_mask:0xf
	v_pk_fma_f32 v[24:25], v[88:89], v[30:31], v[24:25] op_sel_hi:[1,0,1] neg_lo:[0,1,0] neg_hi:[0,1,0]
	v_pk_fma_f32 v[26:27], v[90:91], v[30:31], v[26:27] op_sel_hi:[1,0,1] neg_lo:[0,1,0] neg_hi:[0,1,0]
	ds_read_b128 v[144:147], v195 offset:4864
	ds_read_b128 v[156:159], v195 offset:13056
	ds_read_b128 v[168:171], v195 offset:29440
	ds_read_b128 v[180:183], v195 offset:21248
	ds_read_b128 v[88:91], v195 offset:37632
	ds_read_b64 v[8:9], v196 offset:9728
	ds_read_b64 v[10:11], v36 offset:9728
	s_waitcnt lgkmcnt(7)
	v_pk_mul_f32 v[46:47], v[24:25], v[140:141] op_sel_hi:[0,1]
	v_pk_mul_f32 v[34:35], v[20:21], v[140:141] op_sel_hi:[0,1]
	v_pk_fma_f32 v[46:47], v[24:25], v[142:143], v[46:47] op_sel:[1,0,0] op_sel_hi:[1,1,1]
	v_pk_fma_f32 v[34:35], v[20:21], v[142:143], v[34:35] op_sel:[1,0,0] op_sel_hi:[1,1,1]
	v_pk_fma_f32 v[46:47], v[26:27], v[152:153], v[46:47] op_sel_hi:[0,1,1]
	v_pk_fma_f32 v[34:35], v[22:23], v[152:153], v[34:35] op_sel_hi:[0,1,1]
	v_pk_fma_f32 v[46:47], v[26:27], v[154:155], v[46:47] op_sel:[1,0,0] op_sel_hi:[1,1,1]
	v_pk_fma_f32 v[34:35], v[22:23], v[154:155], v[34:35] op_sel:[1,0,0] op_sel_hi:[1,1,1]
	v_pk_fma_f32 v[20:21], v[176:177], v[4:5], v[20:21] op_sel_hi:[1,0,1]
	v_add_f32_dpp v28, v46, v34 row_half_mirror row_mask:0xf bank_mask:0xf
	v_add_f32_dpp v150, v47, v35 row_half_mirror row_mask:0xf bank_mask:0xf
	v_pk_fma_f32 v[22:23], v[178:179], v[4:5], v[22:23] op_sel_hi:[1,0,1]
	v_add_f32_dpp v28, v28, v28 row_ror:8 row_mask:0xf bank_mask:0xf
	v_pk_fma_f32 v[24:25], v[176:177], v[6:7], v[24:25] op_sel_hi:[1,0,1]
	v_pk_fma_f32 v[26:27], v[178:179], v[6:7], v[26:27] op_sel_hi:[1,0,1]
	v_add_f32_dpp v28, v28, v28 quad_perm:[1,0,3,2] row_mask:0xf bank_mask:0xf
	v_fmac_f32_e32 v150, 0x3e000000, v5
	s_nop 0
	v_add_f32_dpp v28, v28, v28 quad_perm:[2,3,0,1] row_mask:0xf bank_mask:0xf
	v_pk_fma_f32 v[20:21], v[84:85], v[28:29], v[20:21] op_sel_hi:[1,0,1] neg_lo:[0,1,0] neg_hi:[0,1,0]
	v_pk_fma_f32 v[22:23], v[86:87], v[28:29], v[22:23] op_sel_hi:[1,0,1] neg_lo:[0,1,0] neg_hi:[0,1,0]
	v_mov_b32_dpp v30, v28 row_half_mirror row_mask:0xf bank_mask:0xf
	v_pk_fma_f32 v[24:25], v[84:85], v[30:31], v[24:25] op_sel_hi:[1,0,1] neg_lo:[0,1,0] neg_hi:[0,1,0]
	v_pk_fma_f32 v[26:27], v[86:87], v[30:31], v[26:27] op_sel_hi:[1,0,1] neg_lo:[0,1,0] neg_hi:[0,1,0]
	ds_read_b128 v[140:143], v195 offset:5120
	ds_read_b128 v[152:155], v195 offset:13312
	ds_read_b128 v[176:179], v195 offset:21504
	ds_read_b128 v[84:87], v195 offset:37888
	ds_read_b64 v[4:5], v196 offset:10240
	ds_read_b64 v[6:7], v36 offset:10240
	s_waitcnt lgkmcnt(6)
	v_pk_mul_f32 v[46:47], v[24:25], v[144:145] op_sel_hi:[0,1]
	v_pk_mul_f32 v[34:35], v[20:21], v[144:145] op_sel_hi:[0,1]
	v_pk_fma_f32 v[46:47], v[24:25], v[146:147], v[46:47] op_sel:[1,0,0] op_sel_hi:[1,1,1]
	v_pk_fma_f32 v[34:35], v[20:21], v[146:147], v[34:35] op_sel:[1,0,0] op_sel_hi:[1,1,1]
	v_pk_fma_f32 v[46:47], v[26:27], v[156:157], v[46:47] op_sel_hi:[0,1,1]
	v_pk_fma_f32 v[34:35], v[22:23], v[156:157], v[34:35] op_sel_hi:[0,1,1]
	v_pk_fma_f32 v[46:47], v[26:27], v[158:159], v[46:47] op_sel:[1,0,0] op_sel_hi:[1,1,1]
	v_pk_fma_f32 v[34:35], v[22:23], v[158:159], v[34:35] op_sel:[1,0,0] op_sel_hi:[1,1,1]
	v_pk_mul_f32 v[20:21], v[20:21], v[168:169]
	v_add_f32_dpp v28, v46, v34 row_half_mirror row_mask:0xf bank_mask:0xf
	v_add_f32_dpp v151, v47, v35 row_half_mirror row_mask:0xf bank_mask:0xf
	v_pk_mul_f32 v[22:23], v[22:23], v[170:171]
	v_add_f32_dpp v28, v28, v28 row_ror:8 row_mask:0xf bank_mask:0xf
	v_pk_mul_f32 v[24:25], v[24:25], v[168:169]
	v_pk_mul_f32 v[26:27], v[26:27], v[170:171]
	v_add_f32_dpp v28, v28, v28 quad_perm:[1,0,3,2] row_mask:0xf bank_mask:0xf
	v_pk_fma_f32 v[20:21], v[180:181], v[8:9], v[20:21] op_sel_hi:[1,0,1]
	v_pk_fma_f32 v[22:23], v[182:183], v[8:9], v[22:23] op_sel_hi:[1,0,1]
	v_add_f32_dpp v28, v28, v28 quad_perm:[2,3,0,1] row_mask:0xf bank_mask:0xf
	v_pk_fma_f32 v[24:25], v[180:181], v[10:11], v[24:25] op_sel_hi:[1,0,1]
	v_pk_fma_f32 v[26:27], v[182:183], v[10:11], v[26:27] op_sel_hi:[1,0,1]
	v_mov_b32_dpp v30, v28 row_half_mirror row_mask:0xf bank_mask:0xf
	v_fmac_f32_e32 v151, 0x3e000000, v9
	v_pk_fma_f32 v[20:21], v[88:89], v[28:29], v[20:21] op_sel_hi:[1,0,1] neg_lo:[0,1,0] neg_hi:[0,1,0]
	v_pk_fma_f32 v[22:23], v[90:91], v[28:29], v[22:23] op_sel_hi:[1,0,1] neg_lo:[0,1,0] neg_hi:[0,1,0]
	v_pk_fma_f32 v[24:25], v[88:89], v[30:31], v[24:25] op_sel_hi:[1,0,1] neg_lo:[0,1,0] neg_hi:[0,1,0]
	v_pk_fma_f32 v[26:27], v[90:91], v[30:31], v[26:27] op_sel_hi:[1,0,1] neg_lo:[0,1,0] neg_hi:[0,1,0]
	v_add_f32_dpp v160, v148, v148 row_ror:8 row_mask:0xf bank_mask:0x3
	v_add_f32_dpp v160, v149, v149 row_ror:8 row_mask:0xf bank_mask:0xc
	v_add_f32_dpp v161, v150, v150 row_ror:8 row_mask:0xf bank_mask:0x3
	v_add_f32_dpp v161, v151, v151 row_ror:8 row_mask:0xf bank_mask:0xc
	v_add_f32_dpp v160, v160, v160 quad_perm:[1,0,3,2] row_mask:0xf bank_mask:0xf
	s_nop 0
	v_add_f32_dpp v161, v161, v161 quad_perm:[1,0,3,2] row_mask:0xf bank_mask:0xf
	v_add_f32_dpp v160, v160, v160 quad_perm:[2,3,0,1] row_mask:0xf bank_mask:0xf
	s_nop 0
	v_add_f32_dpp v161, v161, v161 quad_perm:[2,3,0,1] row_mask:0xf bank_mask:0xf
	ds_write_b32 v102, v160 offset:2048
	ds_write_b32 v102, v161 offset:2304
	ds_read_b128 v[144:147], v195 offset:5376
	ds_read_b128 v[156:159], v195 offset:13568
	ds_read_b128 v[180:183], v195 offset:21760
	ds_read_b128 v[88:91], v195 offset:38144
	ds_read_b64 v[8:9], v196 offset:10752
	ds_read_b64 v[10:11], v36 offset:10752
	s_waitcnt lgkmcnt(8)
	v_pk_mul_f32 v[46:47], v[24:25], v[140:141] op_sel_hi:[0,1]
	v_pk_mul_f32 v[34:35], v[20:21], v[140:141] op_sel_hi:[0,1]
	v_pk_fma_f32 v[46:47], v[24:25], v[142:143], v[46:47] op_sel:[1,0,0] op_sel_hi:[1,1,1]
	v_pk_fma_f32 v[34:35], v[20:21], v[142:143], v[34:35] op_sel:[1,0,0] op_sel_hi:[1,1,1]
	v_pk_fma_f32 v[46:47], v[26:27], v[152:153], v[46:47] op_sel_hi:[0,1,1]
	v_pk_fma_f32 v[34:35], v[22:23], v[152:153], v[34:35] op_sel_hi:[0,1,1]
	v_pk_fma_f32 v[46:47], v[26:27], v[154:155], v[46:47] op_sel:[1,0,0] op_sel_hi:[1,1,1]
	v_pk_fma_f32 v[34:35], v[22:23], v[154:155], v[34:35] op_sel:[1,0,0] op_sel_hi:[1,1,1]
	v_pk_fma_f32 v[20:21], v[176:177], v[4:5], v[20:21] op_sel_hi:[1,0,1]
	v_add_f32_dpp v28, v46, v34 row_half_mirror row_mask:0xf bank_mask:0xf
	v_add_f32_dpp v148, v47, v35 row_half_mirror row_mask:0xf bank_mask:0xf
	v_pk_fma_f32 v[22:23], v[178:179], v[4:5], v[22:23] op_sel_hi:[1,0,1]
	v_add_f32_dpp v28, v28, v28 row_ror:8 row_mask:0xf bank_mask:0xf
	v_pk_fma_f32 v[24:25], v[176:177], v[6:7], v[24:25] op_sel_hi:[1,0,1]
	v_pk_fma_f32 v[26:27], v[178:179], v[6:7], v[26:27] op_sel_hi:[1,0,1]
	v_add_f32_dpp v28, v28, v28 quad_perm:[1,0,3,2] row_mask:0xf bank_mask:0xf
	v_fmac_f32_e32 v148, 0x3e000000, v5
	s_nop 0
	v_add_f32_dpp v28, v28, v28 quad_perm:[2,3,0,1] row_mask:0xf bank_mask:0xf
	v_pk_fma_f32 v[20:21], v[84:85], v[28:29], v[20:21] op_sel_hi:[1,0,1] neg_lo:[0,1,0] neg_hi:[0,1,0]
	v_pk_fma_f32 v[22:23], v[86:87], v[28:29], v[22:23] op_sel_hi:[1,0,1] neg_lo:[0,1,0] neg_hi:[0,1,0]
	v_mov_b32_dpp v30, v28 row_half_mirror row_mask:0xf bank_mask:0xf
	v_pk_fma_f32 v[24:25], v[84:85], v[30:31], v[24:25] op_sel_hi:[1,0,1] neg_lo:[0,1,0] neg_hi:[0,1,0]
	v_pk_fma_f32 v[26:27], v[86:87], v[30:31], v[26:27] op_sel_hi:[1,0,1] neg_lo:[0,1,0] neg_hi:[0,1,0]
	ds_read_b128 v[140:143], v195 offset:5632
	ds_read_b128 v[152:155], v195 offset:13824
	ds_read_b128 v[176:179], v195 offset:22016
	ds_read_b128 v[84:87], v195 offset:38400
	ds_read_b64 v[4:5], v196 offset:11264
	ds_read_b64 v[6:7], v36 offset:11264
	s_waitcnt lgkmcnt(6)
	v_pk_mul_f32 v[46:47], v[24:25], v[144:145] op_sel_hi:[0,1]
	v_pk_mul_f32 v[34:35], v[20:21], v[144:145] op_sel_hi:[0,1]
	v_pk_fma_f32 v[46:47], v[24:25], v[146:147], v[46:47] op_sel:[1,0,0] op_sel_hi:[1,1,1]
	v_pk_fma_f32 v[34:35], v[20:21], v[146:147], v[34:35] op_sel:[1,0,0] op_sel_hi:[1,1,1]
	v_pk_fma_f32 v[46:47], v[26:27], v[156:157], v[46:47] op_sel_hi:[0,1,1]
	v_pk_fma_f32 v[34:35], v[22:23], v[156:157], v[34:35] op_sel_hi:[0,1,1]
	v_pk_fma_f32 v[46:47], v[26:27], v[158:159], v[46:47] op_sel:[1,0,0] op_sel_hi:[1,1,1]
	v_pk_fma_f32 v[34:35], v[22:23], v[158:159], v[34:35] op_sel:[1,0,0] op_sel_hi:[1,1,1]
	v_pk_fma_f32 v[20:21], v[180:181], v[8:9], v[20:21] op_sel_hi:[1,0,1]
	v_add_f32_dpp v28, v46, v34 row_half_mirror row_mask:0xf bank_mask:0xf
	v_add_f32_dpp v149, v47, v35 row_half_mirror row_mask:0xf bank_mask:0xf
	v_pk_fma_f32 v[22:23], v[182:183], v[8:9], v[22:23] op_sel_hi:[1,0,1]
	v_add_f32_dpp v28, v28, v28 row_ror:8 row_mask:0xf bank_mask:0xf
	v_pk_fma_f32 v[24:25], v[180:181], v[10:11], v[24:25] op_sel_hi:[1,0,1]
	v_pk_fma_f32 v[26:27], v[182:183], v[10:11], v[26:27] op_sel_hi:[1,0,1]
	v_add_f32_dpp v28, v28, v28 quad_perm:[1,0,3,2] row_mask:0xf bank_mask:0xf
	v_fmac_f32_e32 v149, 0x3e000000, v9
	s_nop 0
	v_add_f32_dpp v28, v28, v28 quad_perm:[2,3,0,1] row_mask:0xf bank_mask:0xf
	v_pk_fma_f32 v[20:21], v[88:89], v[28:29], v[20:21] op_sel_hi:[1,0,1] neg_lo:[0,1,0] neg_hi:[0,1,0]
	v_pk_fma_f32 v[22:23], v[90:91], v[28:29], v[22:23] op_sel_hi:[1,0,1] neg_lo:[0,1,0] neg_hi:[0,1,0]
	v_mov_b32_dpp v30, v28 row_half_mirror row_mask:0xf bank_mask:0xf
	v_pk_fma_f32 v[24:25], v[88:89], v[30:31], v[24:25] op_sel_hi:[1,0,1] neg_lo:[0,1,0] neg_hi:[0,1,0]
	v_pk_fma_f32 v[26:27], v[90:91], v[30:31], v[26:27] op_sel_hi:[1,0,1] neg_lo:[0,1,0] neg_hi:[0,1,0]
	ds_read_b128 v[144:147], v195 offset:5888
	ds_read_b128 v[156:159], v195 offset:14080
	ds_read_b128 v[168:171], v195 offset:30464
	ds_read_b128 v[180:183], v195 offset:22272
	ds_read_b128 v[88:91], v195 offset:38656
	ds_read_b64 v[8:9], v196 offset:11776
	ds_read_b64 v[10:11], v36 offset:11776
	s_waitcnt lgkmcnt(7)
	v_pk_mul_f32 v[46:47], v[24:25], v[140:141] op_sel_hi:[0,1]
	v_pk_mul_f32 v[34:35], v[20:21], v[140:141] op_sel_hi:[0,1]
	v_pk_fma_f32 v[46:47], v[24:25], v[142:143], v[46:47] op_sel:[1,0,0] op_sel_hi:[1,1,1]
	v_pk_fma_f32 v[34:35], v[20:21], v[142:143], v[34:35] op_sel:[1,0,0] op_sel_hi:[1,1,1]
	v_pk_fma_f32 v[46:47], v[26:27], v[152:153], v[46:47] op_sel_hi:[0,1,1]
	v_pk_fma_f32 v[34:35], v[22:23], v[152:153], v[34:35] op_sel_hi:[0,1,1]
	v_pk_fma_f32 v[46:47], v[26:27], v[154:155], v[46:47] op_sel:[1,0,0] op_sel_hi:[1,1,1]
	v_pk_fma_f32 v[34:35], v[22:23], v[154:155], v[34:35] op_sel:[1,0,0] op_sel_hi:[1,1,1]
	v_pk_fma_f32 v[20:21], v[176:177], v[4:5], v[20:21] op_sel_hi:[1,0,1]
	v_add_f32_dpp v28, v46, v34 row_half_mirror row_mask:0xf bank_mask:0xf
	v_add_f32_dpp v150, v47, v35 row_half_mirror row_mask:0xf bank_mask:0xf
	v_pk_fma_f32 v[22:23], v[178:179], v[4:5], v[22:23] op_sel_hi:[1,0,1]
	v_add_f32_dpp v28, v28, v28 row_ror:8 row_mask:0xf bank_mask:0xf
	v_pk_fma_f32 v[24:25], v[176:177], v[6:7], v[24:25] op_sel_hi:[1,0,1]
	v_pk_fma_f32 v[26:27], v[178:179], v[6:7], v[26:27] op_sel_hi:[1,0,1]
	v_add_f32_dpp v28, v28, v28 quad_perm:[1,0,3,2] row_mask:0xf bank_mask:0xf
	v_fmac_f32_e32 v150, 0x3e000000, v5
	s_nop 0
	v_add_f32_dpp v28, v28, v28 quad_perm:[2,3,0,1] row_mask:0xf bank_mask:0xf
	v_pk_fma_f32 v[20:21], v[84:85], v[28:29], v[20:21] op_sel_hi:[1,0,1] neg_lo:[0,1,0] neg_hi:[0,1,0]
	v_pk_fma_f32 v[22:23], v[86:87], v[28:29], v[22:23] op_sel_hi:[1,0,1] neg_lo:[0,1,0] neg_hi:[0,1,0]
	v_mov_b32_dpp v30, v28 row_half_mirror row_mask:0xf bank_mask:0xf
	v_pk_fma_f32 v[24:25], v[84:85], v[30:31], v[24:25] op_sel_hi:[1,0,1] neg_lo:[0,1,0] neg_hi:[0,1,0]
	v_pk_fma_f32 v[26:27], v[86:87], v[30:31], v[26:27] op_sel_hi:[1,0,1] neg_lo:[0,1,0] neg_hi:[0,1,0]
	ds_read_b128 v[140:143], v195 offset:6144
	ds_read_b128 v[152:155], v195 offset:14336
	ds_read_b128 v[176:179], v195 offset:22528
	ds_read_b128 v[84:87], v195 offset:38912
	ds_read_b64 v[4:5], v196 offset:12288
	ds_read_b64 v[6:7], v36 offset:12288
	s_waitcnt lgkmcnt(6)
	v_pk_mul_f32 v[46:47], v[24:25], v[144:145] op_sel_hi:[0,1]
	v_pk_mul_f32 v[34:35], v[20:21], v[144:145] op_sel_hi:[0,1]
	v_pk_fma_f32 v[46:47], v[24:25], v[146:147], v[46:47] op_sel:[1,0,0] op_sel_hi:[1,1,1]
	v_pk_fma_f32 v[34:35], v[20:21], v[146:147], v[34:35] op_sel:[1,0,0] op_sel_hi:[1,1,1]
	v_pk_fma_f32 v[46:47], v[26:27], v[156:157], v[46:47] op_sel_hi:[0,1,1]
	v_pk_fma_f32 v[34:35], v[22:23], v[156:157], v[34:35] op_sel_hi:[0,1,1]
	v_pk_fma_f32 v[46:47], v[26:27], v[158:159], v[46:47] op_sel:[1,0,0] op_sel_hi:[1,1,1]
	v_pk_fma_f32 v[34:35], v[22:23], v[158:159], v[34:35] op_sel:[1,0,0] op_sel_hi:[1,1,1]
	v_pk_mul_f32 v[20:21], v[20:21], v[168:169]
	v_add_f32_dpp v28, v46, v34 row_half_mirror row_mask:0xf bank_mask:0xf
	v_add_f32_dpp v151, v47, v35 row_half_mirror row_mask:0xf bank_mask:0xf
	v_pk_mul_f32 v[22:23], v[22:23], v[170:171]
	v_add_f32_dpp v28, v28, v28 row_ror:8 row_mask:0xf bank_mask:0xf
	v_pk_mul_f32 v[24:25], v[24:25], v[168:169]
	v_pk_mul_f32 v[26:27], v[26:27], v[170:171]
	v_add_f32_dpp v28, v28, v28 quad_perm:[1,0,3,2] row_mask:0xf bank_mask:0xf
	v_pk_fma_f32 v[20:21], v[180:181], v[8:9], v[20:21] op_sel_hi:[1,0,1]
	v_pk_fma_f32 v[22:23], v[182:183], v[8:9], v[22:23] op_sel_hi:[1,0,1]
	v_add_f32_dpp v28, v28, v28 quad_perm:[2,3,0,1] row_mask:0xf bank_mask:0xf
	v_pk_fma_f32 v[24:25], v[180:181], v[10:11], v[24:25] op_sel_hi:[1,0,1]
	v_pk_fma_f32 v[26:27], v[182:183], v[10:11], v[26:27] op_sel_hi:[1,0,1]
	v_mov_b32_dpp v30, v28 row_half_mirror row_mask:0xf bank_mask:0xf
	v_fmac_f32_e32 v151, 0x3e000000, v9
	v_pk_fma_f32 v[20:21], v[88:89], v[28:29], v[20:21] op_sel_hi:[1,0,1] neg_lo:[0,1,0] neg_hi:[0,1,0]
	v_pk_fma_f32 v[22:23], v[90:91], v[28:29], v[22:23] op_sel_hi:[1,0,1] neg_lo:[0,1,0] neg_hi:[0,1,0]
	v_pk_fma_f32 v[24:25], v[88:89], v[30:31], v[24:25] op_sel_hi:[1,0,1] neg_lo:[0,1,0] neg_hi:[0,1,0]
	v_pk_fma_f32 v[26:27], v[90:91], v[30:31], v[26:27] op_sel_hi:[1,0,1] neg_lo:[0,1,0] neg_hi:[0,1,0]
	v_add_f32_dpp v160, v148, v148 row_ror:8 row_mask:0xf bank_mask:0x3
	v_add_f32_dpp v160, v149, v149 row_ror:8 row_mask:0xf bank_mask:0xc
	v_add_f32_dpp v161, v150, v150 row_ror:8 row_mask:0xf bank_mask:0x3
	v_add_f32_dpp v161, v151, v151 row_ror:8 row_mask:0xf bank_mask:0xc
	v_add_f32_dpp v160, v160, v160 quad_perm:[1,0,3,2] row_mask:0xf bank_mask:0xf
	s_nop 0
	v_add_f32_dpp v161, v161, v161 quad_perm:[1,0,3,2] row_mask:0xf bank_mask:0xf
	v_add_f32_dpp v160, v160, v160 quad_perm:[2,3,0,1] row_mask:0xf bank_mask:0xf
	s_nop 0
	v_add_f32_dpp v161, v161, v161 quad_perm:[2,3,0,1] row_mask:0xf bank_mask:0xf
	ds_write_b32 v102, v160 offset:2560
	ds_write_b32 v102, v161 offset:2816
	ds_read_b128 v[144:147], v195 offset:6400
	ds_read_b128 v[156:159], v195 offset:14592
	ds_read_b128 v[180:183], v195 offset:22784
	ds_read_b128 v[88:91], v195 offset:39168
	ds_read_b64 v[8:9], v196 offset:12800
	ds_read_b64 v[10:11], v36 offset:12800
	s_waitcnt lgkmcnt(8)
	v_pk_mul_f32 v[46:47], v[24:25], v[140:141] op_sel_hi:[0,1]
	v_pk_mul_f32 v[34:35], v[20:21], v[140:141] op_sel_hi:[0,1]
	v_pk_fma_f32 v[46:47], v[24:25], v[142:143], v[46:47] op_sel:[1,0,0] op_sel_hi:[1,1,1]
	v_pk_fma_f32 v[34:35], v[20:21], v[142:143], v[34:35] op_sel:[1,0,0] op_sel_hi:[1,1,1]
	v_pk_fma_f32 v[46:47], v[26:27], v[152:153], v[46:47] op_sel_hi:[0,1,1]
	v_pk_fma_f32 v[34:35], v[22:23], v[152:153], v[34:35] op_sel_hi:[0,1,1]
	v_pk_fma_f32 v[46:47], v[26:27], v[154:155], v[46:47] op_sel:[1,0,0] op_sel_hi:[1,1,1]
	v_pk_fma_f32 v[34:35], v[22:23], v[154:155], v[34:35] op_sel:[1,0,0] op_sel_hi:[1,1,1]
	v_pk_fma_f32 v[20:21], v[176:177], v[4:5], v[20:21] op_sel_hi:[1,0,1]
	v_add_f32_dpp v28, v46, v34 row_half_mirror row_mask:0xf bank_mask:0xf
	v_add_f32_dpp v148, v47, v35 row_half_mirror row_mask:0xf bank_mask:0xf
	v_pk_fma_f32 v[22:23], v[178:179], v[4:5], v[22:23] op_sel_hi:[1,0,1]
	v_add_f32_dpp v28, v28, v28 row_ror:8 row_mask:0xf bank_mask:0xf
	v_pk_fma_f32 v[24:25], v[176:177], v[6:7], v[24:25] op_sel_hi:[1,0,1]
	v_pk_fma_f32 v[26:27], v[178:179], v[6:7], v[26:27] op_sel_hi:[1,0,1]
	v_add_f32_dpp v28, v28, v28 quad_perm:[1,0,3,2] row_mask:0xf bank_mask:0xf
	v_fmac_f32_e32 v148, 0x3e000000, v5
	s_nop 0
	v_add_f32_dpp v28, v28, v28 quad_perm:[2,3,0,1] row_mask:0xf bank_mask:0xf
	v_pk_fma_f32 v[20:21], v[84:85], v[28:29], v[20:21] op_sel_hi:[1,0,1] neg_lo:[0,1,0] neg_hi:[0,1,0]
	v_pk_fma_f32 v[22:23], v[86:87], v[28:29], v[22:23] op_sel_hi:[1,0,1] neg_lo:[0,1,0] neg_hi:[0,1,0]
	v_mov_b32_dpp v30, v28 row_half_mirror row_mask:0xf bank_mask:0xf
	v_pk_fma_f32 v[24:25], v[84:85], v[30:31], v[24:25] op_sel_hi:[1,0,1] neg_lo:[0,1,0] neg_hi:[0,1,0]
	v_pk_fma_f32 v[26:27], v[86:87], v[30:31], v[26:27] op_sel_hi:[1,0,1] neg_lo:[0,1,0] neg_hi:[0,1,0]
	ds_read_b128 v[140:143], v195 offset:6656
	ds_read_b128 v[152:155], v195 offset:14848
	ds_read_b128 v[176:179], v195 offset:23040
	ds_read_b128 v[84:87], v195 offset:39424
	ds_read_b64 v[4:5], v196 offset:13312
	ds_read_b64 v[6:7], v36 offset:13312
	s_waitcnt lgkmcnt(6)
	v_pk_mul_f32 v[46:47], v[24:25], v[144:145] op_sel_hi:[0,1]
	v_pk_mul_f32 v[34:35], v[20:21], v[144:145] op_sel_hi:[0,1]
	v_pk_fma_f32 v[46:47], v[24:25], v[146:147], v[46:47] op_sel:[1,0,0] op_sel_hi:[1,1,1]
	v_pk_fma_f32 v[34:35], v[20:21], v[146:147], v[34:35] op_sel:[1,0,0] op_sel_hi:[1,1,1]
	v_pk_fma_f32 v[46:47], v[26:27], v[156:157], v[46:47] op_sel_hi:[0,1,1]
	v_pk_fma_f32 v[34:35], v[22:23], v[156:157], v[34:35] op_sel_hi:[0,1,1]
	v_pk_fma_f32 v[46:47], v[26:27], v[158:159], v[46:47] op_sel:[1,0,0] op_sel_hi:[1,1,1]
	v_pk_fma_f32 v[34:35], v[22:23], v[158:159], v[34:35] op_sel:[1,0,0] op_sel_hi:[1,1,1]
	v_pk_fma_f32 v[20:21], v[180:181], v[8:9], v[20:21] op_sel_hi:[1,0,1]
	v_add_f32_dpp v28, v46, v34 row_half_mirror row_mask:0xf bank_mask:0xf
	v_add_f32_dpp v149, v47, v35 row_half_mirror row_mask:0xf bank_mask:0xf
	v_pk_fma_f32 v[22:23], v[182:183], v[8:9], v[22:23] op_sel_hi:[1,0,1]
	v_add_f32_dpp v28, v28, v28 row_ror:8 row_mask:0xf bank_mask:0xf
	v_pk_fma_f32 v[24:25], v[180:181], v[10:11], v[24:25] op_sel_hi:[1,0,1]
	v_pk_fma_f32 v[26:27], v[182:183], v[10:11], v[26:27] op_sel_hi:[1,0,1]
	v_add_f32_dpp v28, v28, v28 quad_perm:[1,0,3,2] row_mask:0xf bank_mask:0xf
	v_fmac_f32_e32 v149, 0x3e000000, v9
	s_nop 0
	v_add_f32_dpp v28, v28, v28 quad_perm:[2,3,0,1] row_mask:0xf bank_mask:0xf
	v_pk_fma_f32 v[20:21], v[88:89], v[28:29], v[20:21] op_sel_hi:[1,0,1] neg_lo:[0,1,0] neg_hi:[0,1,0]
	v_pk_fma_f32 v[22:23], v[90:91], v[28:29], v[22:23] op_sel_hi:[1,0,1] neg_lo:[0,1,0] neg_hi:[0,1,0]
	v_mov_b32_dpp v30, v28 row_half_mirror row_mask:0xf bank_mask:0xf
	v_pk_fma_f32 v[24:25], v[88:89], v[30:31], v[24:25] op_sel_hi:[1,0,1] neg_lo:[0,1,0] neg_hi:[0,1,0]
	v_pk_fma_f32 v[26:27], v[90:91], v[30:31], v[26:27] op_sel_hi:[1,0,1] neg_lo:[0,1,0] neg_hi:[0,1,0]
	ds_read_b128 v[144:147], v195 offset:6912
	ds_read_b128 v[156:159], v195 offset:15104
	ds_read_b128 v[168:171], v195 offset:31488
	ds_read_b128 v[180:183], v195 offset:23296
	ds_read_b128 v[88:91], v195 offset:39680
	ds_read_b64 v[8:9], v196 offset:13824
	ds_read_b64 v[10:11], v36 offset:13824
	s_waitcnt lgkmcnt(7)
	v_pk_mul_f32 v[46:47], v[24:25], v[140:141] op_sel_hi:[0,1]
	v_pk_mul_f32 v[34:35], v[20:21], v[140:141] op_sel_hi:[0,1]
	v_pk_fma_f32 v[46:47], v[24:25], v[142:143], v[46:47] op_sel:[1,0,0] op_sel_hi:[1,1,1]
	v_pk_fma_f32 v[34:35], v[20:21], v[142:143], v[34:35] op_sel:[1,0,0] op_sel_hi:[1,1,1]
	v_pk_fma_f32 v[46:47], v[26:27], v[152:153], v[46:47] op_sel_hi:[0,1,1]
	v_pk_fma_f32 v[34:35], v[22:23], v[152:153], v[34:35] op_sel_hi:[0,1,1]
	v_pk_fma_f32 v[46:47], v[26:27], v[154:155], v[46:47] op_sel:[1,0,0] op_sel_hi:[1,1,1]
	v_pk_fma_f32 v[34:35], v[22:23], v[154:155], v[34:35] op_sel:[1,0,0] op_sel_hi:[1,1,1]
	v_pk_fma_f32 v[20:21], v[176:177], v[4:5], v[20:21] op_sel_hi:[1,0,1]
	v_add_f32_dpp v28, v46, v34 row_half_mirror row_mask:0xf bank_mask:0xf
	v_add_f32_dpp v150, v47, v35 row_half_mirror row_mask:0xf bank_mask:0xf
	v_pk_fma_f32 v[22:23], v[178:179], v[4:5], v[22:23] op_sel_hi:[1,0,1]
	v_add_f32_dpp v28, v28, v28 row_ror:8 row_mask:0xf bank_mask:0xf
	v_pk_fma_f32 v[24:25], v[176:177], v[6:7], v[24:25] op_sel_hi:[1,0,1]
	v_pk_fma_f32 v[26:27], v[178:179], v[6:7], v[26:27] op_sel_hi:[1,0,1]
	v_add_f32_dpp v28, v28, v28 quad_perm:[1,0,3,2] row_mask:0xf bank_mask:0xf
	v_fmac_f32_e32 v150, 0x3e000000, v5
	s_nop 0
	v_add_f32_dpp v28, v28, v28 quad_perm:[2,3,0,1] row_mask:0xf bank_mask:0xf
	v_pk_fma_f32 v[20:21], v[84:85], v[28:29], v[20:21] op_sel_hi:[1,0,1] neg_lo:[0,1,0] neg_hi:[0,1,0]
	v_pk_fma_f32 v[22:23], v[86:87], v[28:29], v[22:23] op_sel_hi:[1,0,1] neg_lo:[0,1,0] neg_hi:[0,1,0]
	v_mov_b32_dpp v30, v28 row_half_mirror row_mask:0xf bank_mask:0xf
	v_pk_fma_f32 v[24:25], v[84:85], v[30:31], v[24:25] op_sel_hi:[1,0,1] neg_lo:[0,1,0] neg_hi:[0,1,0]
	v_pk_fma_f32 v[26:27], v[86:87], v[30:31], v[26:27] op_sel_hi:[1,0,1] neg_lo:[0,1,0] neg_hi:[0,1,0]
	ds_read_b128 v[140:143], v195 offset:7168
	ds_read_b128 v[152:155], v195 offset:15360
	ds_read_b128 v[176:179], v195 offset:23552
	ds_read_b128 v[84:87], v195 offset:39936
	ds_read_b64 v[4:5], v196 offset:14336
	ds_read_b64 v[6:7], v36 offset:14336
	s_waitcnt lgkmcnt(6)
	v_pk_mul_f32 v[46:47], v[24:25], v[144:145] op_sel_hi:[0,1]
	v_pk_mul_f32 v[34:35], v[20:21], v[144:145] op_sel_hi:[0,1]
	v_pk_fma_f32 v[46:47], v[24:25], v[146:147], v[46:47] op_sel:[1,0,0] op_sel_hi:[1,1,1]
	v_pk_fma_f32 v[34:35], v[20:21], v[146:147], v[34:35] op_sel:[1,0,0] op_sel_hi:[1,1,1]
	v_pk_fma_f32 v[46:47], v[26:27], v[156:157], v[46:47] op_sel_hi:[0,1,1]
	v_pk_fma_f32 v[34:35], v[22:23], v[156:157], v[34:35] op_sel_hi:[0,1,1]
	v_pk_fma_f32 v[46:47], v[26:27], v[158:159], v[46:47] op_sel:[1,0,0] op_sel_hi:[1,1,1]
	v_pk_fma_f32 v[34:35], v[22:23], v[158:159], v[34:35] op_sel:[1,0,0] op_sel_hi:[1,1,1]
	v_pk_mul_f32 v[20:21], v[20:21], v[168:169]
	v_add_f32_dpp v28, v46, v34 row_half_mirror row_mask:0xf bank_mask:0xf
	v_add_f32_dpp v151, v47, v35 row_half_mirror row_mask:0xf bank_mask:0xf
	v_pk_mul_f32 v[22:23], v[22:23], v[170:171]
	v_add_f32_dpp v28, v28, v28 row_ror:8 row_mask:0xf bank_mask:0xf
	v_pk_mul_f32 v[24:25], v[24:25], v[168:169]
	v_pk_mul_f32 v[26:27], v[26:27], v[170:171]
	v_add_f32_dpp v28, v28, v28 quad_perm:[1,0,3,2] row_mask:0xf bank_mask:0xf
	v_pk_fma_f32 v[20:21], v[180:181], v[8:9], v[20:21] op_sel_hi:[1,0,1]
	v_pk_fma_f32 v[22:23], v[182:183], v[8:9], v[22:23] op_sel_hi:[1,0,1]
	v_add_f32_dpp v28, v28, v28 quad_perm:[2,3,0,1] row_mask:0xf bank_mask:0xf
	v_pk_fma_f32 v[24:25], v[180:181], v[10:11], v[24:25] op_sel_hi:[1,0,1]
	v_pk_fma_f32 v[26:27], v[182:183], v[10:11], v[26:27] op_sel_hi:[1,0,1]
	v_mov_b32_dpp v30, v28 row_half_mirror row_mask:0xf bank_mask:0xf
	v_fmac_f32_e32 v151, 0x3e000000, v9
	v_pk_fma_f32 v[20:21], v[88:89], v[28:29], v[20:21] op_sel_hi:[1,0,1] neg_lo:[0,1,0] neg_hi:[0,1,0]
	v_pk_fma_f32 v[22:23], v[90:91], v[28:29], v[22:23] op_sel_hi:[1,0,1] neg_lo:[0,1,0] neg_hi:[0,1,0]
	v_pk_fma_f32 v[24:25], v[88:89], v[30:31], v[24:25] op_sel_hi:[1,0,1] neg_lo:[0,1,0] neg_hi:[0,1,0]
	v_pk_fma_f32 v[26:27], v[90:91], v[30:31], v[26:27] op_sel_hi:[1,0,1] neg_lo:[0,1,0] neg_hi:[0,1,0]
	v_add_f32_dpp v160, v148, v148 row_ror:8 row_mask:0xf bank_mask:0x3
	v_add_f32_dpp v160, v149, v149 row_ror:8 row_mask:0xf bank_mask:0xc
	v_add_f32_dpp v161, v150, v150 row_ror:8 row_mask:0xf bank_mask:0x3
	v_add_f32_dpp v161, v151, v151 row_ror:8 row_mask:0xf bank_mask:0xc
	v_add_f32_dpp v160, v160, v160 quad_perm:[1,0,3,2] row_mask:0xf bank_mask:0xf
	s_nop 0
	v_add_f32_dpp v161, v161, v161 quad_perm:[1,0,3,2] row_mask:0xf bank_mask:0xf
	v_add_f32_dpp v160, v160, v160 quad_perm:[2,3,0,1] row_mask:0xf bank_mask:0xf
	s_nop 0
	v_add_f32_dpp v161, v161, v161 quad_perm:[2,3,0,1] row_mask:0xf bank_mask:0xf
	ds_write_b32 v102, v160 offset:3072
	ds_write_b32 v102, v161 offset:3328
	ds_read_b128 v[144:147], v195 offset:7424
	ds_read_b128 v[156:159], v195 offset:15616
	ds_read_b128 v[180:183], v195 offset:23808
	ds_read_b128 v[88:91], v195 offset:40192
	ds_read_b64 v[8:9], v196 offset:14848
	ds_read_b64 v[10:11], v36 offset:14848
	s_waitcnt lgkmcnt(8)
	v_pk_mul_f32 v[46:47], v[24:25], v[140:141] op_sel_hi:[0,1]
	v_pk_mul_f32 v[34:35], v[20:21], v[140:141] op_sel_hi:[0,1]
	v_pk_fma_f32 v[46:47], v[24:25], v[142:143], v[46:47] op_sel:[1,0,0] op_sel_hi:[1,1,1]
	v_pk_fma_f32 v[34:35], v[20:21], v[142:143], v[34:35] op_sel:[1,0,0] op_sel_hi:[1,1,1]
	v_pk_fma_f32 v[46:47], v[26:27], v[152:153], v[46:47] op_sel_hi:[0,1,1]
	v_pk_fma_f32 v[34:35], v[22:23], v[152:153], v[34:35] op_sel_hi:[0,1,1]
	v_pk_fma_f32 v[46:47], v[26:27], v[154:155], v[46:47] op_sel:[1,0,0] op_sel_hi:[1,1,1]
	v_pk_fma_f32 v[34:35], v[22:23], v[154:155], v[34:35] op_sel:[1,0,0] op_sel_hi:[1,1,1]
	v_pk_fma_f32 v[20:21], v[176:177], v[4:5], v[20:21] op_sel_hi:[1,0,1]
	v_add_f32_dpp v28, v46, v34 row_half_mirror row_mask:0xf bank_mask:0xf
	v_add_f32_dpp v148, v47, v35 row_half_mirror row_mask:0xf bank_mask:0xf
	v_pk_fma_f32 v[22:23], v[178:179], v[4:5], v[22:23] op_sel_hi:[1,0,1]
	v_add_f32_dpp v28, v28, v28 row_ror:8 row_mask:0xf bank_mask:0xf
	v_pk_fma_f32 v[24:25], v[176:177], v[6:7], v[24:25] op_sel_hi:[1,0,1]
	v_pk_fma_f32 v[26:27], v[178:179], v[6:7], v[26:27] op_sel_hi:[1,0,1]
	v_add_f32_dpp v28, v28, v28 quad_perm:[1,0,3,2] row_mask:0xf bank_mask:0xf
	v_fmac_f32_e32 v148, 0x3e000000, v5
	s_nop 0
	v_add_f32_dpp v28, v28, v28 quad_perm:[2,3,0,1] row_mask:0xf bank_mask:0xf
	v_pk_fma_f32 v[20:21], v[84:85], v[28:29], v[20:21] op_sel_hi:[1,0,1] neg_lo:[0,1,0] neg_hi:[0,1,0]
	v_pk_fma_f32 v[22:23], v[86:87], v[28:29], v[22:23] op_sel_hi:[1,0,1] neg_lo:[0,1,0] neg_hi:[0,1,0]
	v_mov_b32_dpp v30, v28 row_half_mirror row_mask:0xf bank_mask:0xf
	v_pk_fma_f32 v[24:25], v[84:85], v[30:31], v[24:25] op_sel_hi:[1,0,1] neg_lo:[0,1,0] neg_hi:[0,1,0]
	v_pk_fma_f32 v[26:27], v[86:87], v[30:31], v[26:27] op_sel_hi:[1,0,1] neg_lo:[0,1,0] neg_hi:[0,1,0]
	ds_read_b128 v[140:143], v195 offset:7680
	ds_read_b128 v[152:155], v195 offset:15872
	ds_read_b128 v[176:179], v195 offset:24064
	ds_read_b128 v[84:87], v195 offset:40448
	ds_read_b64 v[4:5], v196 offset:15360
	ds_read_b64 v[6:7], v36 offset:15360
	s_waitcnt lgkmcnt(6)
	v_pk_mul_f32 v[46:47], v[24:25], v[144:145] op_sel_hi:[0,1]
	v_pk_mul_f32 v[34:35], v[20:21], v[144:145] op_sel_hi:[0,1]
	v_pk_fma_f32 v[46:47], v[24:25], v[146:147], v[46:47] op_sel:[1,0,0] op_sel_hi:[1,1,1]
	v_pk_fma_f32 v[34:35], v[20:21], v[146:147], v[34:35] op_sel:[1,0,0] op_sel_hi:[1,1,1]
	v_pk_fma_f32 v[46:47], v[26:27], v[156:157], v[46:47] op_sel_hi:[0,1,1]
	v_pk_fma_f32 v[34:35], v[22:23], v[156:157], v[34:35] op_sel_hi:[0,1,1]
	v_pk_fma_f32 v[46:47], v[26:27], v[158:159], v[46:47] op_sel:[1,0,0] op_sel_hi:[1,1,1]
	v_pk_fma_f32 v[34:35], v[22:23], v[158:159], v[34:35] op_sel:[1,0,0] op_sel_hi:[1,1,1]
	v_pk_fma_f32 v[20:21], v[180:181], v[8:9], v[20:21] op_sel_hi:[1,0,1]
	v_add_f32_dpp v28, v46, v34 row_half_mirror row_mask:0xf bank_mask:0xf
	v_add_f32_dpp v149, v47, v35 row_half_mirror row_mask:0xf bank_mask:0xf
	v_pk_fma_f32 v[22:23], v[182:183], v[8:9], v[22:23] op_sel_hi:[1,0,1]
	v_add_f32_dpp v28, v28, v28 row_ror:8 row_mask:0xf bank_mask:0xf
	v_pk_fma_f32 v[24:25], v[180:181], v[10:11], v[24:25] op_sel_hi:[1,0,1]
	v_pk_fma_f32 v[26:27], v[182:183], v[10:11], v[26:27] op_sel_hi:[1,0,1]
	v_add_f32_dpp v28, v28, v28 quad_perm:[1,0,3,2] row_mask:0xf bank_mask:0xf
	v_fmac_f32_e32 v149, 0x3e000000, v9
	s_nop 0
	v_add_f32_dpp v28, v28, v28 quad_perm:[2,3,0,1] row_mask:0xf bank_mask:0xf
	v_pk_fma_f32 v[20:21], v[88:89], v[28:29], v[20:21] op_sel_hi:[1,0,1] neg_lo:[0,1,0] neg_hi:[0,1,0]
	v_pk_fma_f32 v[22:23], v[90:91], v[28:29], v[22:23] op_sel_hi:[1,0,1] neg_lo:[0,1,0] neg_hi:[0,1,0]
	v_mov_b32_dpp v30, v28 row_half_mirror row_mask:0xf bank_mask:0xf
	v_pk_fma_f32 v[24:25], v[88:89], v[30:31], v[24:25] op_sel_hi:[1,0,1] neg_lo:[0,1,0] neg_hi:[0,1,0]
	v_pk_fma_f32 v[26:27], v[90:91], v[30:31], v[26:27] op_sel_hi:[1,0,1] neg_lo:[0,1,0] neg_hi:[0,1,0]
	ds_read_b128 v[144:147], v195 offset:7936
	ds_read_b128 v[156:159], v195 offset:16128
	ds_read_b128 v[168:171], v195 offset:32512
	ds_read_b128 v[180:183], v195 offset:24320
	ds_read_b128 v[88:91], v195 offset:40704
	ds_read_b64 v[8:9], v196 offset:15872
	ds_read_b64 v[10:11], v36 offset:15872
	s_waitcnt lgkmcnt(7)
	v_pk_mul_f32 v[46:47], v[24:25], v[140:141] op_sel_hi:[0,1]
	v_pk_mul_f32 v[34:35], v[20:21], v[140:141] op_sel_hi:[0,1]
	v_pk_fma_f32 v[46:47], v[24:25], v[142:143], v[46:47] op_sel:[1,0,0] op_sel_hi:[1,1,1]
	v_pk_fma_f32 v[34:35], v[20:21], v[142:143], v[34:35] op_sel:[1,0,0] op_sel_hi:[1,1,1]
	v_pk_fma_f32 v[46:47], v[26:27], v[152:153], v[46:47] op_sel_hi:[0,1,1]
	v_pk_fma_f32 v[34:35], v[22:23], v[152:153], v[34:35] op_sel_hi:[0,1,1]
	v_pk_fma_f32 v[46:47], v[26:27], v[154:155], v[46:47] op_sel:[1,0,0] op_sel_hi:[1,1,1]
	v_pk_fma_f32 v[34:35], v[22:23], v[154:155], v[34:35] op_sel:[1,0,0] op_sel_hi:[1,1,1]
	v_pk_fma_f32 v[20:21], v[176:177], v[4:5], v[20:21] op_sel_hi:[1,0,1]
	v_add_f32_dpp v28, v46, v34 row_half_mirror row_mask:0xf bank_mask:0xf
	v_add_f32_dpp v150, v47, v35 row_half_mirror row_mask:0xf bank_mask:0xf
	v_pk_fma_f32 v[22:23], v[178:179], v[4:5], v[22:23] op_sel_hi:[1,0,1]
	v_add_f32_dpp v28, v28, v28 row_ror:8 row_mask:0xf bank_mask:0xf
	v_pk_fma_f32 v[24:25], v[176:177], v[6:7], v[24:25] op_sel_hi:[1,0,1]
	v_pk_fma_f32 v[26:27], v[178:179], v[6:7], v[26:27] op_sel_hi:[1,0,1]
	v_add_f32_dpp v28, v28, v28 quad_perm:[1,0,3,2] row_mask:0xf bank_mask:0xf
	v_fmac_f32_e32 v150, 0x3e000000, v5
	s_nop 0
	v_add_f32_dpp v28, v28, v28 quad_perm:[2,3,0,1] row_mask:0xf bank_mask:0xf
	v_pk_fma_f32 v[20:21], v[84:85], v[28:29], v[20:21] op_sel_hi:[1,0,1] neg_lo:[0,1,0] neg_hi:[0,1,0]
	v_pk_fma_f32 v[22:23], v[86:87], v[28:29], v[22:23] op_sel_hi:[1,0,1] neg_lo:[0,1,0] neg_hi:[0,1,0]
	v_mov_b32_dpp v30, v28 row_half_mirror row_mask:0xf bank_mask:0xf
	v_pk_fma_f32 v[24:25], v[84:85], v[30:31], v[24:25] op_sel_hi:[1,0,1] neg_lo:[0,1,0] neg_hi:[0,1,0]
	v_pk_fma_f32 v[26:27], v[86:87], v[30:31], v[26:27] op_sel_hi:[1,0,1] neg_lo:[0,1,0] neg_hi:[0,1,0]
	s_waitcnt lgkmcnt(0)
	v_pk_mul_f32 v[46:47], v[24:25], v[144:145] op_sel_hi:[0,1]
	v_pk_mul_f32 v[34:35], v[20:21], v[144:145] op_sel_hi:[0,1]
	v_pk_fma_f32 v[46:47], v[24:25], v[146:147], v[46:47] op_sel:[1,0,0] op_sel_hi:[1,1,1]
	v_pk_fma_f32 v[34:35], v[20:21], v[146:147], v[34:35] op_sel:[1,0,0] op_sel_hi:[1,1,1]
	v_pk_fma_f32 v[46:47], v[26:27], v[156:157], v[46:47] op_sel_hi:[0,1,1]
	v_pk_fma_f32 v[34:35], v[22:23], v[156:157], v[34:35] op_sel_hi:[0,1,1]
	v_pk_fma_f32 v[46:47], v[26:27], v[158:159], v[46:47] op_sel:[1,0,0] op_sel_hi:[1,1,1]
	v_pk_fma_f32 v[34:35], v[22:23], v[158:159], v[34:35] op_sel:[1,0,0] op_sel_hi:[1,1,1]
	v_pk_mul_f32 v[20:21], v[20:21], v[168:169]
	v_add_f32_dpp v28, v46, v34 row_half_mirror row_mask:0xf bank_mask:0xf
	v_add_f32_dpp v151, v47, v35 row_half_mirror row_mask:0xf bank_mask:0xf
	v_pk_mul_f32 v[22:23], v[22:23], v[170:171]
	v_add_f32_dpp v28, v28, v28 row_ror:8 row_mask:0xf bank_mask:0xf
	v_pk_mul_f32 v[24:25], v[24:25], v[168:169]
	v_pk_mul_f32 v[26:27], v[26:27], v[170:171]
	v_add_f32_dpp v28, v28, v28 quad_perm:[1,0,3,2] row_mask:0xf bank_mask:0xf
	v_pk_fma_f32 v[20:21], v[180:181], v[8:9], v[20:21] op_sel_hi:[1,0,1]
	v_pk_fma_f32 v[22:23], v[182:183], v[8:9], v[22:23] op_sel_hi:[1,0,1]
	v_add_f32_dpp v28, v28, v28 quad_perm:[2,3,0,1] row_mask:0xf bank_mask:0xf
	v_pk_fma_f32 v[24:25], v[180:181], v[10:11], v[24:25] op_sel_hi:[1,0,1]
	v_pk_fma_f32 v[26:27], v[182:183], v[10:11], v[26:27] op_sel_hi:[1,0,1]
	v_mov_b32_dpp v30, v28 row_half_mirror row_mask:0xf bank_mask:0xf
	v_fmac_f32_e32 v151, 0x3e000000, v9
	v_pk_fma_f32 v[20:21], v[88:89], v[28:29], v[20:21] op_sel_hi:[1,0,1] neg_lo:[0,1,0] neg_hi:[0,1,0]
	v_pk_fma_f32 v[22:23], v[90:91], v[28:29], v[22:23] op_sel_hi:[1,0,1] neg_lo:[0,1,0] neg_hi:[0,1,0]
	v_pk_fma_f32 v[24:25], v[88:89], v[30:31], v[24:25] op_sel_hi:[1,0,1] neg_lo:[0,1,0] neg_hi:[0,1,0]
	v_pk_fma_f32 v[26:27], v[90:91], v[30:31], v[26:27] op_sel_hi:[1,0,1] neg_lo:[0,1,0] neg_hi:[0,1,0]
	v_add_f32_dpp v160, v148, v148 row_ror:8 row_mask:0xf bank_mask:0x3
	v_add_f32_dpp v160, v149, v149 row_ror:8 row_mask:0xf bank_mask:0xc
	v_add_f32_dpp v161, v150, v150 row_ror:8 row_mask:0xf bank_mask:0x3
	v_add_f32_dpp v161, v151, v151 row_ror:8 row_mask:0xf bank_mask:0xc
	v_add_f32_dpp v160, v160, v160 quad_perm:[1,0,3,2] row_mask:0xf bank_mask:0xf
	s_nop 0
	v_add_f32_dpp v161, v161, v161 quad_perm:[1,0,3,2] row_mask:0xf bank_mask:0xf
	v_add_f32_dpp v160, v160, v160 quad_perm:[2,3,0,1] row_mask:0xf bank_mask:0xf
	s_nop 0
	v_add_f32_dpp v161, v161, v161 quad_perm:[2,3,0,1] row_mask:0xf bank_mask:0xf
	ds_write_b32 v102, v160 offset:3584
	ds_write_b32 v102, v161 offset:3840
	s_waitcnt lgkmcnt(0)
	s_barrier
	s_add_i32 s8, s8, 1
	s_cmp_eq_u32 s8, 64
	s_cbranch_scc0 .Lrw_scan_loop
	s_setprio 0
	s_branch .LBB0_183
